# all six GEMM K-loops: LDS-DMA global addresses in scalar-base + 32-bit lane-offset form (no per-load 64-bit VALU adds)
# speedup vs baseline: 1.0086x; 1.0041x over previous
; #define PG8_STAGE(bufoff, gbase, voff) do { _Pragma("unroll") for (int _i = 0; _i < 2; ++_i) \
;         __builtin_amdgcn_global_load_lds((const unsigned*)((const char*)(gbase) + (voff)[_i]), (LAS unsigned*)(lds + (bufoff) + ldsw + _i * 8192), 16, 0, 0); } while (0)
; #define PG8_LDA(dst, b, h) do { _Pragma("unroll") for (int m = 0; m < 4; ++m) _Pragma("unroll") for (int k = 0; k < 2; ++k) dst[m][k] = *(const LAS bf16x8*)(lds + PG8_SA(b, h) + aoff + m * 2048 + k * 1024); } while (0)
; #define PG8_LDB(dst, b, h) do { _Pragma("unroll") for (int n = 0; n < 2; ++n) _Pragma("unroll") for (int k = 0; k < 2; ++k) dst[n][k] = *(const LAS bf16x8*)(lds + PG8_SB(b, h) + boff + n * 2048 + k * 1024); } while (0)
; #define PG8_MMA(ai, bj, At, Bt) do { __builtin_amdgcn_s_setprio(1); _Pragma("unroll") for (int m = 0; m < 4; ++m) _Pragma("unroll") for (int n = 0; n < 2; ++n) _Pragma("unroll") for (int k = 0; k < 2; ++k) \
;         acc[ai][bj][m][n] = __builtin_amdgcn_mfma_f32_16x16x32_bf16(Bt[n][k], At[m][k], acc[ai][bj][m][n], 0, 0, 0); __builtin_amdgcn_s_setprio(0); } while (0)
; #define PG8_WAIT_V(n) asm volatile("s_waitcnt vmcnt(" #n ")" ::: "memory")
; #define PG8_WAIT_L(n) asm volatile("s_waitcnt lgkmcnt(" #n ")" ::: "memory")
; #define PG8_BAR __builtin_amdgcn_s_barrier()
; template <class Epi, class Sched>
; DI void gemm_phase(LAS unsigned char* lds, const Sched& S, const Epi& E) {
;     ...
;         for (int t = 0; t < nt; t += 2) {
;             const bool last = (t == nt - 2);
;             const char* a1 = cA + (size_t)(t + 1) * kstep;
;             const char* a2 = last ? nA : cA + (size_t)(t + 2) * kstep; const char* b2 = last ? nB : cB + (size_t)(t + 2) * kstep;
;             const char* a3 = a2 + kstep; const char* b3 = b2 + kstep;
;             if constexpr (Epi::HOOK) { if (cur.ks < 0 && (t == 16 || t == 32)) E.hook(acc, cur, t >> 4, wr, wc, fr, fq); }
;             PG8_LDB(B0, 0, 0); PG8_LDB(B1, 0, 1); PG8_SCHED; PG8_LDA(At, 0, 0); PG8_STAGE(PG8_SA(1, 1), a1 + hstepA, voffA);
;             PG8_WAIT_V(8); PG8_WAIT_L(0); PG8_BAR; PG8_MMA(0, 0, At, B0); PG8_MMA(0, 1, At, B1); PG8_BAR; PG8_SCHED;
;             PG8_LDA(At, 0, 1); PG8_STAGE(PG8_SB(0, 0), b2, voffB); PG8_STAGE(PG8_SB(0, 1), b2 + hstepB, voffB); PG8_STAGE(PG8_SA(0, 0), a2, voffA);
;             PG8_WAIT_V(8); PG8_WAIT_L(0); PG8_BAR; PG8_MMA(1, 0, At, B0); PG8_MMA(1, 1, At, B1); PG8_BAR; PG8_SCHED;
.LBB0_156:
	s_add_i32 s82, s8, 2
	s_add_u32 s9, s4, 0xfff80080
	s_addc_u32 s40, s5, -1
	s_add_i32 s83, 0, 0x10000
	s_cmp_eq_u32 s79, s8
	s_cselect_b32 s41, s42, s40
	s_cselect_b32 s40, s43, s9
	v_add_u32_e32 v2, s83, v145
	s_cselect_b32 s9, s53, s81
	s_cselect_b32 s8, s57, s80
	s_add_i32 s85, 0, 0x14000
	ds_read_b128 v[52:55], v2
	ds_read_b128 v[156:159], v2 offset:1024
	ds_read_b128 v[160:163], v2 offset:2048
	ds_read_b128 v[168:171], v2 offset:3072
	v_add_u32_e32 v2, s85, v145
	ds_read_b128 v[172:175], v2
	ds_read_b128 v[176:179], v2 offset:1024
	ds_read_b128 v[180:183], v2 offset:2048
	ds_read_b128 v[184:187], v2 offset:3072
	s_add_i32 m0, s62, 0xc000
	ds_read_b128 v[188:191], v166
	ds_read_b128 v[192:195], v166 offset:1024
	ds_read_b128 v[204:207], v166 offset:2048
	ds_read_b128 v[208:211], v166 offset:3072
	ds_read_b128 v[212:215], v166 offset:4096
	ds_read_b128 v[230:233], v166 offset:5120
	ds_read_b128 v[234:237], v166 offset:6144
	ds_read_b128 v[238:241], v166 offset:7168
	global_load_lds_dwordx4 v154, s[4:5]
	s_add_i32 m0, s62, 0xe000
	s_nop 0
	global_load_lds_dwordx4 v152, s[4:5]
	s_waitcnt vmcnt(8)
	s_waitcnt lgkmcnt(0)
	s_barrier
	s_setprio 1
	s_waitcnt lgkmcnt(0)
	v_mfma_f32_16x16x32_bf16 v[132:135], v[52:55], v[188:191], v[132:135]
	v_mfma_f32_16x16x32_bf16 v[128:131], v[160:163], v[188:191], v[128:131]
	v_mfma_f32_16x16x32_bf16 v[116:119], v[52:55], v[204:207], v[116:119]
	v_mfma_f32_16x16x32_bf16 v[112:115], v[160:163], v[204:207], v[112:115]
	v_mfma_f32_16x16x32_bf16 v[100:103], v[52:55], v[212:215], v[100:103]
	v_mfma_f32_16x16x32_bf16 v[96:99], v[160:163], v[212:215], v[96:99]
	v_mfma_f32_16x16x32_bf16 v[84:87], v[52:55], v[234:237], v[84:87]
	v_mfma_f32_16x16x32_bf16 v[80:83], v[160:163], v[234:237], v[80:83]
	v_mfma_f32_16x16x32_bf16 v[132:135], v[156:159], v[192:195], v[132:135]
	v_mfma_f32_16x16x32_bf16 v[128:131], v[168:171], v[192:195], v[128:131]
	v_mfma_f32_16x16x32_bf16 v[116:119], v[156:159], v[208:211], v[116:119]
	v_mfma_f32_16x16x32_bf16 v[112:115], v[168:171], v[208:211], v[112:115]
	v_mfma_f32_16x16x32_bf16 v[100:103], v[156:159], v[230:233], v[100:103]
	v_mfma_f32_16x16x32_bf16 v[96:99], v[168:171], v[230:233], v[96:99]
	v_mfma_f32_16x16x32_bf16 v[84:87], v[156:159], v[238:241], v[84:87]
	v_mfma_f32_16x16x32_bf16 v[80:83], v[168:171], v[238:241], v[80:83]
	s_setprio 0
	s_setprio 1
	v_mfma_f32_16x16x32_bf16 v[124:127], v[172:175], v[188:191], v[124:127]
	v_mfma_f32_16x16x32_bf16 v[120:123], v[180:183], v[188:191], v[120:123]
	v_mfma_f32_16x16x32_bf16 v[108:111], v[172:175], v[204:207], v[108:111]
	v_mfma_f32_16x16x32_bf16 v[104:107], v[180:183], v[204:207], v[104:107]
	v_mfma_f32_16x16x32_bf16 v[92:95], v[172:175], v[212:215], v[92:95]
	v_mfma_f32_16x16x32_bf16 v[88:91], v[180:183], v[212:215], v[88:91]
	v_mfma_f32_16x16x32_bf16 v[76:79], v[172:175], v[234:237], v[76:79]
	v_mfma_f32_16x16x32_bf16 v[72:75], v[180:183], v[234:237], v[72:75]
	v_mfma_f32_16x16x32_bf16 v[124:127], v[176:179], v[192:195], v[124:127]
	v_mfma_f32_16x16x32_bf16 v[120:123], v[184:187], v[192:195], v[120:123]
	v_mfma_f32_16x16x32_bf16 v[108:111], v[176:179], v[208:211], v[108:111]
	v_mfma_f32_16x16x32_bf16 v[104:107], v[184:187], v[208:211], v[104:107]
	v_mfma_f32_16x16x32_bf16 v[92:95], v[176:179], v[230:233], v[92:95]
	v_mfma_f32_16x16x32_bf16 v[88:91], v[184:187], v[230:233], v[88:91]
	v_mfma_f32_16x16x32_bf16 v[76:79], v[176:179], v[238:241], v[76:79]
	v_mfma_f32_16x16x32_bf16 v[72:75], v[184:187], v[238:241], v[72:75]
	s_setprio 0
	s_barrier
	s_add_i32 s83, s83, s27
	s_mov_b32 m0, s83
	ds_read_b128 v[188:191], v166 offset:16384
	ds_read_b128 v[192:195], v166 offset:17408
	ds_read_b128 v[204:207], v166 offset:18432
	ds_read_b128 v[208:211], v166 offset:19456
	ds_read_b128 v[212:215], v166 offset:20480
	ds_read_b128 v[230:233], v166 offset:21504
	ds_read_b128 v[234:237], v166 offset:22528
	ds_read_b128 v[238:241], v166 offset:23552
	global_load_lds_dwordx4 v138, s[8:9]
	s_add_i32 m0, s83, 0x2000
	s_add_u32 s86, s8, 0x80000
	s_addc_u32 s87, s9, 0
	s_add_i32 s83, s85, s27
	global_load_lds_dwordx4 v142, s[8:9]
	s_mov_b32 m0, s83
	s_nop 0
	global_load_lds_dwordx4 v138, s[86:87]
	s_add_i32 m0, s83, 0x2000
	s_nop 0
	global_load_lds_dwordx4 v142, s[86:87]
	s_add_u32 s98, s40, 0x80
	s_addc_u32 s99, s41, 0
	s_mov_b32 m0, s62
	s_nop 0
	global_load_lds_dwordx4 v136, s[40:41]
	s_mov_b32 m0, s63
	s_nop 0
	global_load_lds_dwordx4 v140, s[40:41]
	s_waitcnt vmcnt(8)
	s_waitcnt lgkmcnt(0)
	s_barrier
	s_setprio 1
	s_waitcnt lgkmcnt(0)
	v_mfma_f32_16x16x32_bf16 v[68:71], v[52:55], v[188:191], v[68:71]
	v_mfma_f32_16x16x32_bf16 v[64:67], v[160:163], v[188:191], v[64:67]
	v_mfma_f32_16x16x32_bf16 v[48:51], v[52:55], v[204:207], v[48:51]
	v_mfma_f32_16x16x32_bf16 v[44:47], v[160:163], v[204:207], v[44:47]
	v_mfma_f32_16x16x32_bf16 v[32:35], v[52:55], v[212:215], v[32:35]
	v_mfma_f32_16x16x32_bf16 v[28:31], v[160:163], v[212:215], v[28:31]
	v_mfma_f32_16x16x32_bf16 v[16:19], v[52:55], v[234:237], v[16:19]
	v_mfma_f32_16x16x32_bf16 v[12:15], v[160:163], v[234:237], v[12:15]
	v_mfma_f32_16x16x32_bf16 v[68:71], v[156:159], v[192:195], v[68:71]
	v_mfma_f32_16x16x32_bf16 v[64:67], v[168:171], v[192:195], v[64:67]
	v_mfma_f32_16x16x32_bf16 v[48:51], v[156:159], v[208:211], v[48:51]
	v_mfma_f32_16x16x32_bf16 v[44:47], v[168:171], v[208:211], v[44:47]
	v_mfma_f32_16x16x32_bf16 v[32:35], v[156:159], v[230:233], v[32:35]
	v_mfma_f32_16x16x32_bf16 v[28:31], v[168:171], v[230:233], v[28:31]
	v_mfma_f32_16x16x32_bf16 v[16:19], v[156:159], v[238:241], v[16:19]
	v_mfma_f32_16x16x32_bf16 v[12:15], v[168:171], v[238:241], v[12:15]
	s_setprio 0
	s_setprio 1
	v_mfma_f32_16x16x32_bf16 v[56:59], v[180:183], v[188:191], v[56:59]
	v_mfma_f32_16x16x32_bf16 v[40:43], v[172:175], v[204:207], v[40:43]
	v_mfma_f32_16x16x32_bf16 v[36:39], v[180:183], v[204:207], v[36:39]
	v_mfma_f32_16x16x32_bf16 v[24:27], v[172:175], v[212:215], v[24:27]
	v_mfma_f32_16x16x32_bf16 v[20:23], v[180:183], v[212:215], v[20:23]
	v_mfma_f32_16x16x32_bf16 v[8:11], v[172:175], v[234:237], v[8:11]
	v_mfma_f32_16x16x32_bf16 v[4:7], v[180:183], v[234:237], v[4:7]
	v_mfma_f32_16x16x32_bf16 v[52:55], v[172:175], v[188:191], v[60:63]
	v_mfma_f32_16x16x32_bf16 v[56:59], v[184:187], v[192:195], v[56:59]
	v_mfma_f32_16x16x32_bf16 v[40:43], v[176:179], v[208:211], v[40:43]
	v_mfma_f32_16x16x32_bf16 v[36:39], v[184:187], v[208:211], v[36:39]
	v_mfma_f32_16x16x32_bf16 v[24:27], v[176:179], v[230:233], v[24:27]
	v_mfma_f32_16x16x32_bf16 v[20:23], v[184:187], v[230:233], v[20:23]
	v_mfma_f32_16x16x32_bf16 v[8:11], v[176:179], v[238:241], v[8:11]
	v_mfma_f32_16x16x32_bf16 v[4:7], v[184:187], v[238:241], v[4:7]
	v_mfma_f32_16x16x32_bf16 v[52:55], v[176:179], v[192:195], v[52:55]
	s_setprio 0
	s_barrier
; #define PG8_STAGE(bufoff, gbase, voff) do { _Pragma("unroll") for (int _i = 0; _i < 2; ++_i) \
;         __builtin_amdgcn_global_load_lds((const unsigned*)((const char*)(gbase) + (voff)[_i]), (LAS unsigned*)(lds + (bufoff) + ldsw + _i * 8192), 16, 0, 0); } while (0)
; #define PG8_LDA(dst, b, h) do { _Pragma("unroll") for (int m = 0; m < 4; ++m) _Pragma("unroll") for (int k = 0; k < 2; ++k) dst[m][k] = *(const LAS bf16x8*)(lds + PG8_SA(b, h) + aoff + m * 2048 + k * 1024); } while (0)
; #define PG8_LDB(dst, b, h) do { _Pragma("unroll") for (int n = 0; n < 2; ++n) _Pragma("unroll") for (int k = 0; k < 2; ++k) dst[n][k] = *(const LAS bf16x8*)(lds + PG8_SB(b, h) + boff + n * 2048 + k * 1024); } while (0)
; #define PG8_MMA(ai, bj, At, Bt) do { __builtin_amdgcn_s_setprio(1); _Pragma("unroll") for (int m = 0; m < 4; ++m) _Pragma("unroll") for (int n = 0; n < 2; ++n) _Pragma("unroll") for (int k = 0; k < 2; ++k) \
;         acc[ai][bj][m][n] = __builtin_amdgcn_mfma_f32_16x16x32_bf16(Bt[n][k], At[m][k], acc[ai][bj][m][n], 0, 0, 0); __builtin_amdgcn_s_setprio(0); } while (0)
; #define PG8_WAIT_V(n) asm volatile("s_waitcnt vmcnt(" #n ")" ::: "memory")
; #define PG8_WAIT_L(n) asm volatile("s_waitcnt lgkmcnt(" #n ")" ::: "memory")
; #define PG8_BAR __builtin_amdgcn_s_barrier()
; #define PG8_SCHED __builtin_amdgcn_sched_barrier(0)
; template <class Epi, class Sched>
; DI void gemm_phase(LAS unsigned char* lds, const Sched& S, const Epi& E) {
;     ...
;             PG8_LDB(B0, 1, 0); PG8_LDB(B1, 1, 1); PG8_SCHED; PG8_LDA(At, 1, 0); PG8_STAGE(PG8_SA(0, 1), a2 + hstepA, voffA);
;             PG8_WAIT_V(8); PG8_WAIT_L(0); PG8_BAR; PG8_MMA(0, 0, At, B0); PG8_MMA(0, 1, At, B1); PG8_BAR; PG8_SCHED;
;             PG8_LDA(At, 1, 1); PG8_STAGE(PG8_SB(1, 0), b3, voffB); PG8_STAGE(PG8_SB(1, 1), b3 + hstepB, voffB); PG8_STAGE(PG8_SA(1, 0), a3, voffA);
;             PG8_WAIT_V(8); PG8_WAIT_L(0); PG8_BAR; PG8_MMA(1, 0, At, B0); PG8_MMA(1, 1, At, B1); PG8_BAR; PG8_SCHED;
;         }
	s_add_i32 s83, 0, 0x18000
	v_add_u32_e32 v2, s83, v145
	s_add_i32 s85, 0, 0x1c000
	ds_read_b128 v[60:63], v2
	ds_read_b128 v[156:159], v2 offset:1024
	ds_read_b128 v[160:163], v2 offset:2048
	ds_read_b128 v[168:171], v2 offset:3072
	v_add_u32_e32 v2, s85, v145
	ds_read_b128 v[172:175], v2
	ds_read_b128 v[176:179], v2 offset:1024
	ds_read_b128 v[180:183], v2 offset:2048
	ds_read_b128 v[184:187], v2 offset:3072
	s_add_u32 s40, s40, 0x80000
	s_addc_u32 s41, s41, 0
	s_mov_b32 m0, s64
	ds_read_b128 v[188:191], v166 offset:32768
	ds_read_b128 v[192:195], v166 offset:33792
	ds_read_b128 v[204:207], v166 offset:34816
	ds_read_b128 v[208:211], v166 offset:35840
	ds_read_b128 v[212:215], v166 offset:36864
	ds_read_b128 v[230:233], v166 offset:37888
	ds_read_b128 v[234:237], v166 offset:38912
	ds_read_b128 v[238:241], v166 offset:39936
	global_load_lds_dwordx4 v136, s[40:41]
	s_mov_b32 m0, s65
	s_nop 0
	global_load_lds_dwordx4 v140, s[40:41]
	s_waitcnt vmcnt(8)
	s_waitcnt lgkmcnt(0)
	s_barrier
	s_setprio 1
	s_waitcnt lgkmcnt(0)
	v_mfma_f32_16x16x32_bf16 v[132:135], v[60:63], v[188:191], v[132:135]
	v_mfma_f32_16x16x32_bf16 v[128:131], v[160:163], v[188:191], v[128:131]
	v_mfma_f32_16x16x32_bf16 v[116:119], v[60:63], v[204:207], v[116:119]
	v_mfma_f32_16x16x32_bf16 v[112:115], v[160:163], v[204:207], v[112:115]
	v_mfma_f32_16x16x32_bf16 v[100:103], v[60:63], v[212:215], v[100:103]
	v_mfma_f32_16x16x32_bf16 v[96:99], v[160:163], v[212:215], v[96:99]
	v_mfma_f32_16x16x32_bf16 v[84:87], v[60:63], v[234:237], v[84:87]
	v_mfma_f32_16x16x32_bf16 v[80:83], v[160:163], v[234:237], v[80:83]
	v_mfma_f32_16x16x32_bf16 v[132:135], v[156:159], v[192:195], v[132:135]
	v_mfma_f32_16x16x32_bf16 v[128:131], v[168:171], v[192:195], v[128:131]
	v_mfma_f32_16x16x32_bf16 v[116:119], v[156:159], v[208:211], v[116:119]
	v_mfma_f32_16x16x32_bf16 v[112:115], v[168:171], v[208:211], v[112:115]
	v_mfma_f32_16x16x32_bf16 v[100:103], v[156:159], v[230:233], v[100:103]
	v_mfma_f32_16x16x32_bf16 v[96:99], v[168:171], v[230:233], v[96:99]
	v_mfma_f32_16x16x32_bf16 v[84:87], v[156:159], v[238:241], v[84:87]
	v_mfma_f32_16x16x32_bf16 v[80:83], v[168:171], v[238:241], v[80:83]
	s_setprio 0
	s_setprio 1
	v_mfma_f32_16x16x32_bf16 v[124:127], v[172:175], v[188:191], v[124:127]
	v_mfma_f32_16x16x32_bf16 v[120:123], v[180:183], v[188:191], v[120:123]
	v_mfma_f32_16x16x32_bf16 v[108:111], v[172:175], v[204:207], v[108:111]
	v_mfma_f32_16x16x32_bf16 v[104:107], v[180:183], v[204:207], v[104:107]
	v_mfma_f32_16x16x32_bf16 v[92:95], v[172:175], v[212:215], v[92:95]
	v_mfma_f32_16x16x32_bf16 v[88:91], v[180:183], v[212:215], v[88:91]
	v_mfma_f32_16x16x32_bf16 v[76:79], v[172:175], v[234:237], v[76:79]
	v_mfma_f32_16x16x32_bf16 v[72:75], v[180:183], v[234:237], v[72:75]
	v_mfma_f32_16x16x32_bf16 v[124:127], v[176:179], v[192:195], v[124:127]
	v_mfma_f32_16x16x32_bf16 v[120:123], v[184:187], v[192:195], v[120:123]
	v_mfma_f32_16x16x32_bf16 v[108:111], v[176:179], v[208:211], v[108:111]
	v_mfma_f32_16x16x32_bf16 v[104:107], v[184:187], v[208:211], v[104:107]
	v_mfma_f32_16x16x32_bf16 v[92:95], v[176:179], v[230:233], v[92:95]
	v_mfma_f32_16x16x32_bf16 v[88:91], v[184:187], v[230:233], v[88:91]
	v_mfma_f32_16x16x32_bf16 v[76:79], v[176:179], v[238:241], v[76:79]
	v_mfma_f32_16x16x32_bf16 v[72:75], v[184:187], v[238:241], v[72:75]
	s_setprio 0
	s_barrier
	s_add_i32 s40, s83, s27
	s_add_u32 s8, s8, 0x80
	s_addc_u32 s9, s9, 0
	s_mov_b32 m0, s40
	ds_read_b128 v[188:191], v166 offset:49152
	ds_read_b128 v[192:195], v166 offset:50176
	ds_read_b128 v[204:207], v166 offset:51200
	ds_read_b128 v[208:211], v166 offset:52224
	ds_read_b128 v[212:215], v166 offset:53248
	ds_read_b128 v[230:233], v166 offset:54272
	ds_read_b128 v[234:237], v166 offset:55296
	ds_read_b128 v[238:241], v166 offset:56320
	global_load_lds_dwordx4 v138, s[8:9]
	s_add_i32 m0, s40, 0x2000
	s_add_i32 s40, s85, s27
	global_load_lds_dwordx4 v142, s[8:9]
	s_add_u32 s8, s8, 0x80000
	s_addc_u32 s9, s9, 0
	s_mov_b32 m0, s40
	s_nop 0
	global_load_lds_dwordx4 v138, s[8:9]
	s_add_i32 m0, s40, 0x2000
	s_nop 0
	global_load_lds_dwordx4 v142, s[8:9]
	s_mov_b32 m0, s72
	s_nop 0
	global_load_lds_dwordx4 v136, s[98:99]
	s_mov_b32 m0, s73
	s_nop 0
	global_load_lds_dwordx4 v140, s[98:99]
	s_waitcnt vmcnt(8)
	s_waitcnt lgkmcnt(0)
	s_barrier
	s_setprio 1
	s_waitcnt lgkmcnt(0)
	v_mfma_f32_16x16x32_bf16 v[68:71], v[60:63], v[188:191], v[68:71]
	v_mfma_f32_16x16x32_bf16 v[64:67], v[160:163], v[188:191], v[64:67]
	v_mfma_f32_16x16x32_bf16 v[48:51], v[60:63], v[204:207], v[48:51]
	v_mfma_f32_16x16x32_bf16 v[44:47], v[160:163], v[204:207], v[44:47]
	v_mfma_f32_16x16x32_bf16 v[32:35], v[60:63], v[212:215], v[32:35]
	v_mfma_f32_16x16x32_bf16 v[28:31], v[160:163], v[212:215], v[28:31]
	v_mfma_f32_16x16x32_bf16 v[16:19], v[60:63], v[234:237], v[16:19]
	v_mfma_f32_16x16x32_bf16 v[12:15], v[160:163], v[234:237], v[12:15]
	v_mfma_f32_16x16x32_bf16 v[68:71], v[156:159], v[192:195], v[68:71]
	v_mfma_f32_16x16x32_bf16 v[64:67], v[168:171], v[192:195], v[64:67]
	v_mfma_f32_16x16x32_bf16 v[48:51], v[156:159], v[208:211], v[48:51]
	v_mfma_f32_16x16x32_bf16 v[44:47], v[168:171], v[208:211], v[44:47]
	v_mfma_f32_16x16x32_bf16 v[32:35], v[156:159], v[230:233], v[32:35]
	v_mfma_f32_16x16x32_bf16 v[28:31], v[168:171], v[230:233], v[28:31]
	v_mfma_f32_16x16x32_bf16 v[16:19], v[156:159], v[238:241], v[16:19]
	v_mfma_f32_16x16x32_bf16 v[12:15], v[168:171], v[238:241], v[12:15]
	s_setprio 0
	s_setprio 1
	v_mfma_f32_16x16x32_bf16 v[52:55], v[172:175], v[188:191], v[52:55]
	v_mfma_f32_16x16x32_bf16 v[60:63], v[176:179], v[192:195], v[52:55]
	v_mfma_f32_16x16x32_bf16 v[52:55], v[180:183], v[188:191], v[56:59]
	v_mfma_f32_16x16x32_bf16 v[40:43], v[172:175], v[204:207], v[40:43]
	v_mfma_f32_16x16x32_bf16 v[36:39], v[180:183], v[204:207], v[36:39]
	v_mfma_f32_16x16x32_bf16 v[24:27], v[172:175], v[212:215], v[24:27]
	v_mfma_f32_16x16x32_bf16 v[20:23], v[180:183], v[212:215], v[20:23]
	v_mfma_f32_16x16x32_bf16 v[8:11], v[172:175], v[234:237], v[8:11]
	v_mfma_f32_16x16x32_bf16 v[4:7], v[180:183], v[234:237], v[4:7]
	v_mfma_f32_16x16x32_bf16 v[56:59], v[184:187], v[192:195], v[52:55]
	v_mfma_f32_16x16x32_bf16 v[40:43], v[176:179], v[208:211], v[40:43]
	v_mfma_f32_16x16x32_bf16 v[36:39], v[184:187], v[208:211], v[36:39]
	v_mfma_f32_16x16x32_bf16 v[24:27], v[176:179], v[230:233], v[24:27]
	v_mfma_f32_16x16x32_bf16 v[20:23], v[184:187], v[230:233], v[20:23]
	v_mfma_f32_16x16x32_bf16 v[8:11], v[176:179], v[238:241], v[8:11]
	v_mfma_f32_16x16x32_bf16 v[4:7], v[184:187], v[238:241], v[4:7]
	s_setprio 0
	s_barrier
	s_add_u32 s80, s80, 0x100
	s_addc_u32 s81, s81, 0
	s_add_u32 s4, s4, 0x100
	s_addc_u32 s5, s5, 0
	s_cmp_ge_i32 s82, s35
	s_mov_b32 s8, s82
	s_cbranch_scc0 .LBB0_156
	s_and_b64 vcc, exec, s[48:49]
	s_cbranch_vccz .LBB0_159
	s_barrier

; #define PG8_STAGE(bufoff, gbase, voff) do { _Pragma("unroll") for (int _i = 0; _i < 2; ++_i) \
;         __builtin_amdgcn_global_load_lds((const unsigned*)((const char*)(gbase) + (voff)[_i]), (LAS unsigned*)(lds + (bufoff) + ldsw + _i * 8192), 16, 0, 0); } while (0)
; #define PG8_LDA(dst, b, h) do { _Pragma("unroll") for (int m = 0; m < 4; ++m) _Pragma("unroll") for (int k = 0; k < 2; ++k) dst[m][k] = *(const LAS bf16x8*)(lds + PG8_SA(b, h) + aoff + m * 2048 + k * 1024); } while (0)
; #define PG8_LDB(dst, b, h) do { _Pragma("unroll") for (int n = 0; n < 2; ++n) _Pragma("unroll") for (int k = 0; k < 2; ++k) dst[n][k] = *(const LAS bf16x8*)(lds + PG8_SB(b, h) + boff + n * 2048 + k * 1024); } while (0)
; #define PG8_MMA(ai, bj, At, Bt) do { __builtin_amdgcn_s_setprio(1); _Pragma("unroll") for (int m = 0; m < 4; ++m) _Pragma("unroll") for (int n = 0; n < 2; ++n) _Pragma("unroll") for (int k = 0; k < 2; ++k) \
;         acc[ai][bj][m][n] = __builtin_amdgcn_mfma_f32_16x16x32_bf16(Bt[n][k], At[m][k], acc[ai][bj][m][n], 0, 0, 0); __builtin_amdgcn_s_setprio(0); } while (0)
; #define PG8_WAIT_V(n) asm volatile("s_waitcnt vmcnt(" #n ")" ::: "memory")
; #define PG8_WAIT_L(n) asm volatile("s_waitcnt lgkmcnt(" #n ")" ::: "memory")
; #define PG8_BAR __builtin_amdgcn_s_barrier()
; template <class Epi, class Sched>
; DI void gemm_phase(LAS unsigned char* lds, const Sched& S, const Epi& E) {
;     ...
;         for (int t = 0; t < nt; t += 2) {
;             const bool last = (t == nt - 2);
;             const char* a1 = cA + (size_t)(t + 1) * kstep;
;             const char* a2 = last ? nA : cA + (size_t)(t + 2) * kstep; const char* b2 = last ? nB : cB + (size_t)(t + 2) * kstep;
;             const char* a3 = a2 + kstep; const char* b3 = b2 + kstep;
;             if constexpr (Epi::HOOK) { if (cur.ks < 0 && (t == 16 || t == 32)) E.hook(acc, cur, t >> 4, wr, wc, fr, fq); }
;             PG8_LDB(B0, 0, 0); PG8_LDB(B1, 0, 1); PG8_SCHED; PG8_LDA(At, 0, 0); PG8_STAGE(PG8_SA(1, 1), a1 + hstepA, voffA);
;             PG8_WAIT_V(8); PG8_WAIT_L(0); PG8_BAR; PG8_MMA(0, 0, At, B0); PG8_MMA(0, 1, At, B1); PG8_BAR; PG8_SCHED;
;             PG8_LDA(At, 0, 1); PG8_STAGE(PG8_SB(0, 0), b2, voffB); PG8_STAGE(PG8_SB(0, 1), b2 + hstepB, voffB); PG8_STAGE(PG8_SA(0, 0), a2, voffA);
;             PG8_WAIT_V(8); PG8_WAIT_L(0); PG8_BAR; PG8_MMA(1, 0, At, B0); PG8_MMA(1, 1, At, B1); PG8_BAR; PG8_SCHED;
.LBB0_906:
	s_add_i32 s23, s18, 2
	s_add_u32 s4, s40, 0x100
	s_addc_u32 s5, s41, 0
	s_cmp_eq_u32 s97, s18
	s_cselect_b32 s19, s79, s5
	s_cselect_b32 s18, s26, s4
	s_cselect_b32 s9, s27, s67
	s_cselect_b32 s8, s80, s66
	s_add_i32 s85, 0, 0x10000
	v_add_u32_e32 v2, s85, v162
	s_add_i32 vcc_lo, 0, 0x14000
	ds_read_b128 v[134:137], v2
	ds_read_b128 v[138:141], v2 offset:1024
	ds_read_b128 v[166:169], v2 offset:2048
	ds_read_b128 v[170:173], v2 offset:3072
	v_add_u32_e32 v2, vcc_lo, v162
	ds_read_b128 v[174:177], v2
	ds_read_b128 v[178:181], v2 offset:1024
	ds_read_b128 v[182:185], v2 offset:2048
	ds_read_b128 v[186:189], v2 offset:3072
	s_add_i32 m0, s39, 0xc000
	ds_read_b128 v[190:193], v164
	ds_read_b128 v[204:207], v164 offset:1024
	ds_read_b128 v[208:211], v164 offset:2048
	ds_read_b128 v[212:215], v164 offset:3072
	ds_read_b128 v[230:233], v164 offset:4096
	ds_read_b128 v[234:237], v164 offset:5120
	ds_read_b128 v[238:241], v164 offset:6144
	ds_read_b128 v[242:245], v164 offset:7168
	global_load_lds_dwordx4 v156, s[40:41]
	s_add_i32 m0, s39, 0xe000
	s_nop 0
	global_load_lds_dwordx4 v154, s[40:41]
	s_waitcnt vmcnt(8)
	s_waitcnt lgkmcnt(0)
	s_barrier
	s_setprio 1
	s_waitcnt lgkmcnt(0)
	v_mfma_f32_16x16x32_bf16 v[130:133], v[134:137], v[190:193], v[130:133]
	v_mfma_f32_16x16x32_bf16 v[126:129], v[166:169], v[190:193], v[126:129]
	v_mfma_f32_16x16x32_bf16 v[114:117], v[134:137], v[208:211], v[114:117]
	v_mfma_f32_16x16x32_bf16 v[110:113], v[166:169], v[208:211], v[110:113]
	v_mfma_f32_16x16x32_bf16 v[98:101], v[134:137], v[230:233], v[98:101]
	v_mfma_f32_16x16x32_bf16 v[94:97], v[166:169], v[230:233], v[94:97]
	v_mfma_f32_16x16x32_bf16 v[82:85], v[134:137], v[238:241], v[82:85]
	v_mfma_f32_16x16x32_bf16 v[78:81], v[166:169], v[238:241], v[78:81]
	v_mfma_f32_16x16x32_bf16 v[130:133], v[138:141], v[204:207], v[130:133]
	v_mfma_f32_16x16x32_bf16 v[126:129], v[170:173], v[204:207], v[126:129]
	v_mfma_f32_16x16x32_bf16 v[114:117], v[138:141], v[212:215], v[114:117]
	v_mfma_f32_16x16x32_bf16 v[110:113], v[170:173], v[212:215], v[110:113]
	v_mfma_f32_16x16x32_bf16 v[98:101], v[138:141], v[234:237], v[98:101]
	v_mfma_f32_16x16x32_bf16 v[94:97], v[170:173], v[234:237], v[94:97]
	v_mfma_f32_16x16x32_bf16 v[82:85], v[138:141], v[242:245], v[82:85]
	v_mfma_f32_16x16x32_bf16 v[78:81], v[170:173], v[242:245], v[78:81]
	s_setprio 0
	s_setprio 1
	v_mfma_f32_16x16x32_bf16 v[122:125], v[174:177], v[190:193], v[122:125]
	v_mfma_f32_16x16x32_bf16 v[118:121], v[182:185], v[190:193], v[118:121]
	v_mfma_f32_16x16x32_bf16 v[106:109], v[174:177], v[208:211], v[106:109]
	v_mfma_f32_16x16x32_bf16 v[102:105], v[182:185], v[208:211], v[102:105]
	v_mfma_f32_16x16x32_bf16 v[90:93], v[174:177], v[230:233], v[90:93]
	v_mfma_f32_16x16x32_bf16 v[86:89], v[182:185], v[230:233], v[86:89]
	v_mfma_f32_16x16x32_bf16 v[74:77], v[174:177], v[238:241], v[74:77]
	v_mfma_f32_16x16x32_bf16 v[70:73], v[182:185], v[238:241], v[70:73]
	v_mfma_f32_16x16x32_bf16 v[122:125], v[178:181], v[204:207], v[122:125]
	v_mfma_f32_16x16x32_bf16 v[118:121], v[186:189], v[204:207], v[118:121]
	v_mfma_f32_16x16x32_bf16 v[106:109], v[178:181], v[212:215], v[106:109]
	v_mfma_f32_16x16x32_bf16 v[102:105], v[186:189], v[212:215], v[102:105]
	v_mfma_f32_16x16x32_bf16 v[90:93], v[178:181], v[234:237], v[90:93]
	v_mfma_f32_16x16x32_bf16 v[86:89], v[186:189], v[234:237], v[86:89]
	v_mfma_f32_16x16x32_bf16 v[74:77], v[178:181], v[242:245], v[74:77]
	v_mfma_f32_16x16x32_bf16 v[70:73], v[186:189], v[242:245], v[70:73]
	s_setprio 0
	s_barrier
	s_add_i32 s40, s85, s38
	s_mov_b32 m0, s40
	ds_read_b128 v[190:193], v164 offset:16384
	ds_read_b128 v[204:207], v164 offset:17408
	ds_read_b128 v[208:211], v164 offset:18432
	ds_read_b128 v[212:215], v164 offset:19456
	ds_read_b128 v[230:233], v164 offset:20480
	ds_read_b128 v[234:237], v164 offset:21504
	ds_read_b128 v[238:241], v164 offset:22528
	ds_read_b128 v[242:245], v164 offset:23552
	global_load_lds_dwordx4 v144, s[8:9]
	s_add_i32 m0, s40, 0x2000
	s_add_u32 s40, s8, 0xc0000
	s_addc_u32 s41, s9, 0
	s_add_i32 s85, vcc_lo, s38
	global_load_lds_dwordx4 v148, s[8:9]
	s_mov_b32 m0, s85
	s_nop 0
	global_load_lds_dwordx4 v144, s[40:41]
	s_add_i32 m0, s85, 0x2000
	s_nop 0
	global_load_lds_dwordx4 v148, s[40:41]
	s_add_u32 s98, s18, 0x80
	s_addc_u32 s99, s19, 0
	s_mov_b32 m0, s39
	s_nop 0
	global_load_lds_dwordx4 v142, s[18:19]
	s_mov_b32 m0, s63
	s_nop 0
	global_load_lds_dwordx4 v146, s[18:19]
	s_waitcnt vmcnt(8)
	s_waitcnt lgkmcnt(0)
	s_barrier
	s_setprio 1
	s_waitcnt lgkmcnt(0)
	v_mfma_f32_16x16x32_bf16 v[66:69], v[134:137], v[190:193], v[66:69]
	v_mfma_f32_16x16x32_bf16 v[62:65], v[166:169], v[190:193], v[62:65]
	v_mfma_f32_16x16x32_bf16 v[50:53], v[134:137], v[208:211], v[50:53]
	v_mfma_f32_16x16x32_bf16 v[46:49], v[166:169], v[208:211], v[46:49]
	v_mfma_f32_16x16x32_bf16 v[34:37], v[134:137], v[230:233], v[34:37]
	v_mfma_f32_16x16x32_bf16 v[30:33], v[166:169], v[230:233], v[30:33]
	v_mfma_f32_16x16x32_bf16 v[18:21], v[134:137], v[238:241], v[18:21]
	v_mfma_f32_16x16x32_bf16 v[14:17], v[166:169], v[238:241], v[14:17]
	v_mfma_f32_16x16x32_bf16 v[66:69], v[138:141], v[204:207], v[66:69]
	v_mfma_f32_16x16x32_bf16 v[62:65], v[170:173], v[204:207], v[62:65]
	v_mfma_f32_16x16x32_bf16 v[50:53], v[138:141], v[212:215], v[50:53]
	v_mfma_f32_16x16x32_bf16 v[46:49], v[170:173], v[212:215], v[46:49]
	v_mfma_f32_16x16x32_bf16 v[34:37], v[138:141], v[234:237], v[34:37]
	v_mfma_f32_16x16x32_bf16 v[30:33], v[170:173], v[234:237], v[30:33]
	v_mfma_f32_16x16x32_bf16 v[18:21], v[138:141], v[242:245], v[18:21]
	v_mfma_f32_16x16x32_bf16 v[14:17], v[170:173], v[242:245], v[14:17]
	s_setprio 0
	s_setprio 1
	v_mfma_f32_16x16x32_bf16 v[58:61], v[174:177], v[190:193], v[58:61]
	v_mfma_f32_16x16x32_bf16 v[54:57], v[182:185], v[190:193], v[54:57]
	v_mfma_f32_16x16x32_bf16 v[42:45], v[174:177], v[208:211], v[42:45]
	v_mfma_f32_16x16x32_bf16 v[38:41], v[182:185], v[208:211], v[38:41]
	v_mfma_f32_16x16x32_bf16 v[26:29], v[174:177], v[230:233], v[26:29]
	v_mfma_f32_16x16x32_bf16 v[22:25], v[182:185], v[230:233], v[22:25]
	v_mfma_f32_16x16x32_bf16 v[10:13], v[174:177], v[238:241], v[10:13]
	v_mfma_f32_16x16x32_bf16 v[4:7], v[182:185], v[238:241], v[6:9]
	v_mfma_f32_16x16x32_bf16 v[58:61], v[178:181], v[204:207], v[58:61]
	v_mfma_f32_16x16x32_bf16 v[54:57], v[186:189], v[204:207], v[54:57]
	v_mfma_f32_16x16x32_bf16 v[42:45], v[178:181], v[212:215], v[42:45]
	v_mfma_f32_16x16x32_bf16 v[38:41], v[186:189], v[212:215], v[38:41]
	v_mfma_f32_16x16x32_bf16 v[26:29], v[178:181], v[234:237], v[26:29]
	v_mfma_f32_16x16x32_bf16 v[22:25], v[186:189], v[234:237], v[22:25]
	v_mfma_f32_16x16x32_bf16 v[10:13], v[178:181], v[242:245], v[10:13]
	v_mfma_f32_16x16x32_bf16 v[4:7], v[186:189], v[242:245], v[4:7]
	s_setprio 0
	s_barrier
; #define PG8_STAGE(bufoff, gbase, voff) do { _Pragma("unroll") for (int _i = 0; _i < 2; ++_i) \
;         __builtin_amdgcn_global_load_lds((const unsigned*)((const char*)(gbase) + (voff)[_i]), (LAS unsigned*)(lds + (bufoff) + ldsw + _i * 8192), 16, 0, 0); } while (0)
; #define PG8_LDA(dst, b, h) do { _Pragma("unroll") for (int m = 0; m < 4; ++m) _Pragma("unroll") for (int k = 0; k < 2; ++k) dst[m][k] = *(const LAS bf16x8*)(lds + PG8_SA(b, h) + aoff + m * 2048 + k * 1024); } while (0)
; #define PG8_LDB(dst, b, h) do { _Pragma("unroll") for (int n = 0; n < 2; ++n) _Pragma("unroll") for (int k = 0; k < 2; ++k) dst[n][k] = *(const LAS bf16x8*)(lds + PG8_SB(b, h) + boff + n * 2048 + k * 1024); } while (0)
; #define PG8_MMA(ai, bj, At, Bt) do { __builtin_amdgcn_s_setprio(1); _Pragma("unroll") for (int m = 0; m < 4; ++m) _Pragma("unroll") for (int n = 0; n < 2; ++n) _Pragma("unroll") for (int k = 0; k < 2; ++k) \
;         acc[ai][bj][m][n] = __builtin_amdgcn_mfma_f32_16x16x32_bf16(Bt[n][k], At[m][k], acc[ai][bj][m][n], 0, 0, 0); __builtin_amdgcn_s_setprio(0); } while (0)
; #define PG8_WAIT_V(n) asm volatile("s_waitcnt vmcnt(" #n ")" ::: "memory")
; #define PG8_WAIT_L(n) asm volatile("s_waitcnt lgkmcnt(" #n ")" ::: "memory")
; #define PG8_BAR __builtin_amdgcn_s_barrier()
; #define PG8_SCHED __builtin_amdgcn_sched_barrier(0)
; template <class Epi, class Sched>
; DI void gemm_phase(LAS unsigned char* lds, const Sched& S, const Epi& E) {
;     ...
;             PG8_LDB(B0, 1, 0); PG8_LDB(B1, 1, 1); PG8_SCHED; PG8_LDA(At, 1, 0); PG8_STAGE(PG8_SA(0, 1), a2 + hstepA, voffA);
;             PG8_WAIT_V(8); PG8_WAIT_L(0); PG8_BAR; PG8_MMA(0, 0, At, B0); PG8_MMA(0, 1, At, B1); PG8_BAR; PG8_SCHED;
;             PG8_LDA(At, 1, 1); PG8_STAGE(PG8_SB(1, 0), b3, voffB); PG8_STAGE(PG8_SB(1, 1), b3 + hstepB, voffB); PG8_STAGE(PG8_SA(1, 0), a3, voffA);
;             PG8_WAIT_V(8); PG8_WAIT_L(0); PG8_BAR; PG8_MMA(1, 0, At, B0); PG8_MMA(1, 1, At, B1); PG8_BAR; PG8_SCHED;
;         }
	s_add_i32 s40, 0, 0x18000
	v_add_u32_e32 v2, s40, v162
	s_add_i32 s41, 0, 0x1c000
	ds_read_b128 v[134:137], v2
	ds_read_b128 v[138:141], v2 offset:1024
	ds_read_b128 v[166:169], v2 offset:2048
	ds_read_b128 v[170:173], v2 offset:3072
	v_add_u32_e32 v2, s41, v162
	ds_read_b128 v[174:177], v2
	ds_read_b128 v[178:181], v2 offset:1024
	ds_read_b128 v[182:185], v2 offset:2048
	ds_read_b128 v[186:189], v2 offset:3072
	s_add_u32 s18, s18, 0xc0000
	s_addc_u32 s19, s19, 0
	s_mov_b32 m0, s64
	ds_read_b128 v[190:193], v164 offset:32768
	ds_read_b128 v[204:207], v164 offset:33792
	ds_read_b128 v[208:211], v164 offset:34816
	ds_read_b128 v[212:215], v164 offset:35840
	ds_read_b128 v[230:233], v164 offset:36864
	ds_read_b128 v[234:237], v164 offset:37888
	ds_read_b128 v[238:241], v164 offset:38912
	ds_read_b128 v[242:245], v164 offset:39936
	global_load_lds_dwordx4 v142, s[18:19]
	s_mov_b32 m0, s65
	s_nop 0
	global_load_lds_dwordx4 v146, s[18:19]
	s_waitcnt vmcnt(8)
	s_waitcnt lgkmcnt(0)
	s_barrier
	s_setprio 1
	s_waitcnt lgkmcnt(0)
	v_mfma_f32_16x16x32_bf16 v[130:133], v[134:137], v[190:193], v[130:133]
	v_mfma_f32_16x16x32_bf16 v[126:129], v[166:169], v[190:193], v[126:129]
	v_mfma_f32_16x16x32_bf16 v[114:117], v[134:137], v[208:211], v[114:117]
	v_mfma_f32_16x16x32_bf16 v[110:113], v[166:169], v[208:211], v[110:113]
	v_mfma_f32_16x16x32_bf16 v[98:101], v[134:137], v[230:233], v[98:101]
	v_mfma_f32_16x16x32_bf16 v[94:97], v[166:169], v[230:233], v[94:97]
	v_mfma_f32_16x16x32_bf16 v[82:85], v[134:137], v[238:241], v[82:85]
	v_mfma_f32_16x16x32_bf16 v[78:81], v[166:169], v[238:241], v[78:81]
	v_mfma_f32_16x16x32_bf16 v[130:133], v[138:141], v[204:207], v[130:133]
	v_mfma_f32_16x16x32_bf16 v[126:129], v[170:173], v[204:207], v[126:129]
	v_mfma_f32_16x16x32_bf16 v[114:117], v[138:141], v[212:215], v[114:117]
	v_mfma_f32_16x16x32_bf16 v[110:113], v[170:173], v[212:215], v[110:113]
	v_mfma_f32_16x16x32_bf16 v[98:101], v[138:141], v[234:237], v[98:101]
	v_mfma_f32_16x16x32_bf16 v[94:97], v[170:173], v[234:237], v[94:97]
	v_mfma_f32_16x16x32_bf16 v[82:85], v[138:141], v[242:245], v[82:85]
	v_mfma_f32_16x16x32_bf16 v[78:81], v[170:173], v[242:245], v[78:81]
	s_setprio 0
	s_setprio 1
	v_mfma_f32_16x16x32_bf16 v[122:125], v[174:177], v[190:193], v[122:125]
	v_mfma_f32_16x16x32_bf16 v[118:121], v[182:185], v[190:193], v[118:121]
	v_mfma_f32_16x16x32_bf16 v[106:109], v[174:177], v[208:211], v[106:109]
	v_mfma_f32_16x16x32_bf16 v[102:105], v[182:185], v[208:211], v[102:105]
	v_mfma_f32_16x16x32_bf16 v[90:93], v[174:177], v[230:233], v[90:93]
	v_mfma_f32_16x16x32_bf16 v[86:89], v[182:185], v[230:233], v[86:89]
	v_mfma_f32_16x16x32_bf16 v[74:77], v[174:177], v[238:241], v[74:77]
	v_mfma_f32_16x16x32_bf16 v[70:73], v[182:185], v[238:241], v[70:73]
	v_mfma_f32_16x16x32_bf16 v[122:125], v[178:181], v[204:207], v[122:125]
	v_mfma_f32_16x16x32_bf16 v[118:121], v[186:189], v[204:207], v[118:121]
	v_mfma_f32_16x16x32_bf16 v[106:109], v[178:181], v[212:215], v[106:109]
	v_mfma_f32_16x16x32_bf16 v[102:105], v[186:189], v[212:215], v[102:105]
	v_mfma_f32_16x16x32_bf16 v[90:93], v[178:181], v[234:237], v[90:93]
	v_mfma_f32_16x16x32_bf16 v[86:89], v[186:189], v[234:237], v[86:89]
	v_mfma_f32_16x16x32_bf16 v[74:77], v[178:181], v[242:245], v[74:77]
	v_mfma_f32_16x16x32_bf16 v[70:73], v[186:189], v[242:245], v[70:73]
	s_setprio 0
	s_barrier
	s_add_i32 s18, s40, s38
	s_add_u32 s8, s8, 0x80
	s_addc_u32 s9, s9, 0
	s_mov_b32 m0, s18
	ds_read_b128 v[190:193], v164 offset:49152
	ds_read_b128 v[204:207], v164 offset:50176
	ds_read_b128 v[208:211], v164 offset:51200
	ds_read_b128 v[212:215], v164 offset:52224
	ds_read_b128 v[230:233], v164 offset:53248
	ds_read_b128 v[234:237], v164 offset:54272
	ds_read_b128 v[238:241], v164 offset:55296
	ds_read_b128 v[242:245], v164 offset:56320
	global_load_lds_dwordx4 v144, s[8:9]
	s_add_i32 m0, s18, 0x2000
	s_add_i32 s18, s41, s38
	global_load_lds_dwordx4 v148, s[8:9]
	s_add_u32 s8, s8, 0xc0000
	s_addc_u32 s9, s9, 0
	s_mov_b32 m0, s18
	s_nop 0
	global_load_lds_dwordx4 v144, s[8:9]
	s_add_i32 m0, s18, 0x2000
	s_nop 0
	global_load_lds_dwordx4 v148, s[8:9]
	s_mov_b32 m0, s75
	s_nop 0
	global_load_lds_dwordx4 v142, s[98:99]
	s_mov_b32 m0, s81
	s_nop 0
	global_load_lds_dwordx4 v146, s[98:99]
	s_waitcnt vmcnt(8)
	s_waitcnt lgkmcnt(0)
	s_barrier
	s_setprio 1
	s_waitcnt lgkmcnt(0)
	v_mfma_f32_16x16x32_bf16 v[66:69], v[134:137], v[190:193], v[66:69]
	v_mfma_f32_16x16x32_bf16 v[62:65], v[166:169], v[190:193], v[62:65]
	v_mfma_f32_16x16x32_bf16 v[50:53], v[134:137], v[208:211], v[50:53]
	v_mfma_f32_16x16x32_bf16 v[46:49], v[166:169], v[208:211], v[46:49]
	v_mfma_f32_16x16x32_bf16 v[34:37], v[134:137], v[230:233], v[34:37]
	v_mfma_f32_16x16x32_bf16 v[30:33], v[166:169], v[230:233], v[30:33]
	v_mfma_f32_16x16x32_bf16 v[18:21], v[134:137], v[238:241], v[18:21]
	v_mfma_f32_16x16x32_bf16 v[14:17], v[166:169], v[238:241], v[14:17]
	v_mfma_f32_16x16x32_bf16 v[66:69], v[138:141], v[204:207], v[66:69]
	v_mfma_f32_16x16x32_bf16 v[62:65], v[170:173], v[204:207], v[62:65]
	v_mfma_f32_16x16x32_bf16 v[50:53], v[138:141], v[212:215], v[50:53]
	v_mfma_f32_16x16x32_bf16 v[46:49], v[170:173], v[212:215], v[46:49]
	v_mfma_f32_16x16x32_bf16 v[34:37], v[138:141], v[234:237], v[34:37]
	v_mfma_f32_16x16x32_bf16 v[30:33], v[170:173], v[234:237], v[30:33]
	v_mfma_f32_16x16x32_bf16 v[18:21], v[138:141], v[242:245], v[18:21]
	v_mfma_f32_16x16x32_bf16 v[14:17], v[170:173], v[242:245], v[14:17]
	s_setprio 0
	s_setprio 1
	v_mfma_f32_16x16x32_bf16 v[58:61], v[174:177], v[190:193], v[58:61]
	v_mfma_f32_16x16x32_bf16 v[54:57], v[182:185], v[190:193], v[54:57]
	v_mfma_f32_16x16x32_bf16 v[42:45], v[174:177], v[208:211], v[42:45]
	v_mfma_f32_16x16x32_bf16 v[38:41], v[182:185], v[208:211], v[38:41]
	v_mfma_f32_16x16x32_bf16 v[26:29], v[174:177], v[230:233], v[26:29]
	v_mfma_f32_16x16x32_bf16 v[22:25], v[182:185], v[230:233], v[22:25]
	v_mfma_f32_16x16x32_bf16 v[8:11], v[174:177], v[238:241], v[10:13]
	v_mfma_f32_16x16x32_bf16 v[4:7], v[182:185], v[238:241], v[4:7]
	v_mfma_f32_16x16x32_bf16 v[58:61], v[178:181], v[204:207], v[58:61]
	v_mfma_f32_16x16x32_bf16 v[54:57], v[186:189], v[204:207], v[54:57]
	v_mfma_f32_16x16x32_bf16 v[42:45], v[178:181], v[212:215], v[42:45]
	v_mfma_f32_16x16x32_bf16 v[38:41], v[186:189], v[212:215], v[38:41]
	v_mfma_f32_16x16x32_bf16 v[26:29], v[178:181], v[234:237], v[26:29]
	v_mfma_f32_16x16x32_bf16 v[22:25], v[186:189], v[234:237], v[22:25]
	v_mfma_f32_16x16x32_bf16 v[10:13], v[178:181], v[242:245], v[8:11]
	v_mfma_f32_16x16x32_bf16 v[6:9], v[186:189], v[242:245], v[4:7]
	s_setprio 0
	s_barrier
	s_add_i32 s22, s22, 1
	s_add_u32 s66, s66, 0x100
	s_addc_u32 s67, s67, 0
	s_cmp_ge_i32 s23, s10
	s_cbranch_scc1 .LBB0_908
	s_mov_b64 s[40:41], s[4:5]
	s_mov_b32 s18, s23
	s_andn2_b64 vcc, exec, s[56:57]
	s_cbranch_vccnz .LBB0_906
	s_branch .LBB0_900

; #define PG8_STAGE(bufoff, gbase, voff) do { _Pragma("unroll") for (int _i = 0; _i < 2; ++_i) \
;         __builtin_amdgcn_global_load_lds((const unsigned*)((const char*)(gbase) + (voff)[_i]), (LAS unsigned*)(lds + (bufoff) + ldsw + _i * 8192), 16, 0, 0); } while (0)
; #define PG8_LDA(dst, b, h) do { _Pragma("unroll") for (int m = 0; m < 4; ++m) _Pragma("unroll") for (int k = 0; k < 2; ++k) dst[m][k] = *(const LAS bf16x8*)(lds + PG8_SA(b, h) + aoff + m * 2048 + k * 1024); } while (0)
; #define PG8_LDB(dst, b, h) do { _Pragma("unroll") for (int n = 0; n < 2; ++n) _Pragma("unroll") for (int k = 0; k < 2; ++k) dst[n][k] = *(const LAS bf16x8*)(lds + PG8_SB(b, h) + boff + n * 2048 + k * 1024); } while (0)
; #define PG8_MMA(ai, bj, At, Bt) do { __builtin_amdgcn_s_setprio(1); _Pragma("unroll") for (int m = 0; m < 4; ++m) _Pragma("unroll") for (int n = 0; n < 2; ++n) _Pragma("unroll") for (int k = 0; k < 2; ++k) \
;         acc[ai][bj][m][n] = __builtin_amdgcn_mfma_f32_16x16x32_bf16(Bt[n][k], At[m][k], acc[ai][bj][m][n], 0, 0, 0); __builtin_amdgcn_s_setprio(0); } while (0)
; #define PG8_WAIT_V(n) asm volatile("s_waitcnt vmcnt(" #n ")" ::: "memory")
; #define PG8_WAIT_L(n) asm volatile("s_waitcnt lgkmcnt(" #n ")" ::: "memory")
; #define PG8_BAR __builtin_amdgcn_s_barrier()
; template <class Epi, class Sched>
; DI void gemm_phase(LAS unsigned char* lds, const Sched& S, const Epi& E) {
;     ...
;             const bool last = (t == nt - 2);
;             const char* a1 = cA + (size_t)(t + 1) * kstep;
;             const char* a2 = last ? nA : cA + (size_t)(t + 2) * kstep; const char* b2 = last ? nB : cB + (size_t)(t + 2) * kstep;
;             const char* a3 = a2 + kstep; const char* b3 = b2 + kstep;
;             if constexpr (Epi::HOOK) { if (cur.ks < 0 && (t == 16 || t == 32)) E.hook(acc, cur, t >> 4, wr, wc, fr, fq); }
;             PG8_LDB(B0, 0, 0); PG8_LDB(B1, 0, 1); PG8_SCHED; PG8_LDA(At, 0, 0); PG8_STAGE(PG8_SA(1, 1), a1 + hstepA, voffA);
;             PG8_WAIT_V(8); PG8_WAIT_L(0); PG8_BAR; PG8_MMA(0, 0, At, B0); PG8_MMA(0, 1, At, B1); PG8_BAR; PG8_SCHED;
;             PG8_LDA(At, 0, 1); PG8_STAGE(PG8_SB(0, 0), b2, voffB); PG8_STAGE(PG8_SB(0, 1), b2 + hstepB, voffB); PG8_STAGE(PG8_SA(0, 0), a2, voffA);
;             PG8_WAIT_V(8); PG8_WAIT_L(0); PG8_BAR; PG8_MMA(1, 0, At, B0); PG8_MMA(1, 1, At, B1); PG8_BAR; PG8_SCHED;
.LBB0_1104:
	s_add_i32 s82, s52, 2
	s_add_u32 s53, s42, 0xfff80080
	s_addc_u32 s54, s43, -1
	s_add_i32 s83, 0, 0x10000
	s_cmp_eq_u32 s79, s52
	s_cselect_b32 s55, s56, s54
	s_cselect_b32 s54, s57, s53
	s_cselect_b32 s53, s58, s81
	s_cselect_b32 s52, s59, s80
	s_add_i32 s85, 0, 0x14000
	s_waitcnt vmcnt(0)
	v_add_u32_e32 v112, s83, v197
	v_add_u32_e32 v160, s85, v197
	ds_read_b128 v[84:87], v112
	ds_read_b128 v[88:91], v112 offset:1024
	ds_read_b128 v[104:107], v112 offset:2048
	ds_read_b128 v[112:115], v112 offset:3072
	ds_read_b128 v[124:127], v160
	ds_read_b128 v[136:139], v160 offset:1024
	ds_read_b128 v[148:151], v160 offset:2048
	ds_read_b128 v[160:163], v160 offset:3072
	s_add_i32 m0, s26, 0xc000
	ds_read_b128 v[164:167], v231
	ds_read_b128 v[168:171], v231 offset:1024
	ds_read_b128 v[172:175], v231 offset:2048
	ds_read_b128 v[176:179], v231 offset:3072
	ds_read_b128 v[180:183], v231 offset:4096
	ds_read_b128 v[184:187], v231 offset:5120
	ds_read_b128 v[188:191], v231 offset:6144
	ds_read_b128 v[192:195], v231 offset:7168
	global_load_lds_dwordx4 v212, s[42:43]
	s_add_i32 m0, s26, 0xe000
	s_nop 0
	global_load_lds_dwordx4 v210, s[42:43]
	s_waitcnt vmcnt(8)
	s_waitcnt lgkmcnt(0)
	s_barrier
	s_setprio 1
	s_waitcnt lgkmcnt(0)
	v_mfma_f32_16x16x32_bf16 v[156:159], v[84:87], v[164:167], v[156:159]
	v_mfma_f32_16x16x32_bf16 v[152:155], v[104:107], v[164:167], v[152:155]
	v_mfma_f32_16x16x32_bf16 v[132:135], v[84:87], v[172:175], v[132:135]
	v_mfma_f32_16x16x32_bf16 v[128:131], v[104:107], v[172:175], v[128:131]
	v_mfma_f32_16x16x32_bf16 v[108:111], v[84:87], v[180:183], v[108:111]
	v_mfma_f32_16x16x32_bf16 v[100:103], v[104:107], v[180:183], v[100:103]
	v_mfma_f32_16x16x32_bf16 v[80:83], v[84:87], v[188:191], v[80:83]
	v_mfma_f32_16x16x32_bf16 v[76:79], v[104:107], v[188:191], v[76:79]
	v_mfma_f32_16x16x32_bf16 v[156:159], v[88:91], v[168:171], v[156:159]
	v_mfma_f32_16x16x32_bf16 v[152:155], v[112:115], v[168:171], v[152:155]
	v_mfma_f32_16x16x32_bf16 v[132:135], v[88:91], v[176:179], v[132:135]
	v_mfma_f32_16x16x32_bf16 v[128:131], v[112:115], v[176:179], v[128:131]
	v_mfma_f32_16x16x32_bf16 v[108:111], v[88:91], v[184:187], v[108:111]
	v_mfma_f32_16x16x32_bf16 v[100:103], v[112:115], v[184:187], v[100:103]
	v_mfma_f32_16x16x32_bf16 v[80:83], v[88:91], v[192:195], v[80:83]
	v_mfma_f32_16x16x32_bf16 v[76:79], v[112:115], v[192:195], v[76:79]
	s_setprio 0
	s_setprio 1
	v_mfma_f32_16x16x32_bf16 v[144:147], v[124:127], v[164:167], v[144:147]
	v_mfma_f32_16x16x32_bf16 v[140:143], v[148:151], v[164:167], v[140:143]
	v_mfma_f32_16x16x32_bf16 v[120:123], v[124:127], v[172:175], v[120:123]
	v_mfma_f32_16x16x32_bf16 v[116:119], v[148:151], v[172:175], v[116:119]
	v_mfma_f32_16x16x32_bf16 v[96:99], v[124:127], v[180:183], v[96:99]
	v_mfma_f32_16x16x32_bf16 v[92:95], v[148:151], v[180:183], v[92:95]
	v_mfma_f32_16x16x32_bf16 v[72:75], v[124:127], v[188:191], v[72:75]
	v_mfma_f32_16x16x32_bf16 v[68:71], v[148:151], v[188:191], v[68:71]
	v_mfma_f32_16x16x32_bf16 v[144:147], v[136:139], v[168:171], v[144:147]
	v_mfma_f32_16x16x32_bf16 v[140:143], v[160:163], v[168:171], v[140:143]
	v_mfma_f32_16x16x32_bf16 v[120:123], v[136:139], v[176:179], v[120:123]
	v_mfma_f32_16x16x32_bf16 v[116:119], v[160:163], v[176:179], v[116:119]
	v_mfma_f32_16x16x32_bf16 v[96:99], v[136:139], v[184:187], v[96:99]
	v_mfma_f32_16x16x32_bf16 v[92:95], v[160:163], v[184:187], v[92:95]
	v_mfma_f32_16x16x32_bf16 v[72:75], v[136:139], v[192:195], v[72:75]
	v_mfma_f32_16x16x32_bf16 v[68:71], v[160:163], v[192:195], v[68:71]
	s_setprio 0
	s_barrier
	s_add_i32 s83, s83, s23
	s_mov_b32 m0, s83
	ds_read_b128 v[164:167], v231 offset:16384
	ds_read_b128 v[168:171], v231 offset:17408
	ds_read_b128 v[172:175], v231 offset:18432
	ds_read_b128 v[176:179], v231 offset:19456
	ds_read_b128 v[180:183], v231 offset:20480
	ds_read_b128 v[184:187], v231 offset:21504
	ds_read_b128 v[188:191], v231 offset:22528
	ds_read_b128 v[192:195], v231 offset:23552
	global_load_lds_dwordx4 v2, s[52:53]
	s_add_i32 m0, s83, 0x2000
	s_add_u32 s86, s52, 0x80000
	s_addc_u32 s87, s53, 0
	s_add_i32 s83, s85, s23
	global_load_lds_dwordx4 v208, s[52:53]
	s_mov_b32 m0, s83
	s_nop 0
	global_load_lds_dwordx4 v2, s[86:87]
	s_add_i32 m0, s83, 0x2000
	s_nop 0
	global_load_lds_dwordx4 v208, s[86:87]
	s_add_u32 s98, s54, 0x80
	s_addc_u32 s99, s55, 0
	s_mov_b32 m0, s26
	s_nop 0
	global_load_lds_dwordx4 v204, s[54:55]
	s_mov_b32 m0, s27
	s_nop 0
	global_load_lds_dwordx4 v206, s[54:55]
	s_waitcnt vmcnt(8)
	s_waitcnt lgkmcnt(0)
	s_barrier
; #define PG8_STAGE(bufoff, gbase, voff) do { _Pragma("unroll") for (int _i = 0; _i < 2; ++_i) \
;         __builtin_amdgcn_global_load_lds((const unsigned*)((const char*)(gbase) + (voff)[_i]), (LAS unsigned*)(lds + (bufoff) + ldsw + _i * 8192), 16, 0, 0); } while (0)
; #define PG8_LDA(dst, b, h) do { _Pragma("unroll") for (int m = 0; m < 4; ++m) _Pragma("unroll") for (int k = 0; k < 2; ++k) dst[m][k] = *(const LAS bf16x8*)(lds + PG8_SA(b, h) + aoff + m * 2048 + k * 1024); } while (0)
; #define PG8_LDB(dst, b, h) do { _Pragma("unroll") for (int n = 0; n < 2; ++n) _Pragma("unroll") for (int k = 0; k < 2; ++k) dst[n][k] = *(const LAS bf16x8*)(lds + PG8_SB(b, h) + boff + n * 2048 + k * 1024); } while (0)
; #define PG8_MMA(ai, bj, At, Bt) do { __builtin_amdgcn_s_setprio(1); _Pragma("unroll") for (int m = 0; m < 4; ++m) _Pragma("unroll") for (int n = 0; n < 2; ++n) _Pragma("unroll") for (int k = 0; k < 2; ++k) \
;         acc[ai][bj][m][n] = __builtin_amdgcn_mfma_f32_16x16x32_bf16(Bt[n][k], At[m][k], acc[ai][bj][m][n], 0, 0, 0); __builtin_amdgcn_s_setprio(0); } while (0)
; #define PG8_WAIT_V(n) asm volatile("s_waitcnt vmcnt(" #n ")" ::: "memory")
; #define PG8_WAIT_L(n) asm volatile("s_waitcnt lgkmcnt(" #n ")" ::: "memory")
; #define PG8_BAR __builtin_amdgcn_s_barrier()
; #define PG8_SCHED __builtin_amdgcn_sched_barrier(0)
; template <class Epi, class Sched>
; DI void gemm_phase(LAS unsigned char* lds, const Sched& S, const Epi& E) {
;     ...
;             PG8_WAIT_V(8); PG8_WAIT_L(0); PG8_BAR; PG8_MMA(1, 0, At, B0); PG8_MMA(1, 1, At, B1); PG8_BAR; PG8_SCHED;
;             PG8_LDB(B0, 1, 0); PG8_LDB(B1, 1, 1); PG8_SCHED; PG8_LDA(At, 1, 0); PG8_STAGE(PG8_SA(0, 1), a2 + hstepA, voffA);
;             PG8_WAIT_V(8); PG8_WAIT_L(0); PG8_BAR; PG8_MMA(0, 0, At, B0); PG8_MMA(0, 1, At, B1); PG8_BAR; PG8_SCHED;
	s_setprio 1
	s_waitcnt lgkmcnt(0)
	v_mfma_f32_16x16x32_bf16 v[64:67], v[84:87], v[164:167], v[64:67]
	v_mfma_f32_16x16x32_bf16 v[60:63], v[104:107], v[164:167], v[60:63]
	v_mfma_f32_16x16x32_bf16 v[48:51], v[84:87], v[172:175], v[48:51]
	v_mfma_f32_16x16x32_bf16 v[44:47], v[104:107], v[172:175], v[44:47]
	v_mfma_f32_16x16x32_bf16 v[32:35], v[84:87], v[180:183], v[32:35]
	v_mfma_f32_16x16x32_bf16 v[28:31], v[104:107], v[180:183], v[28:31]
	v_mfma_f32_16x16x32_bf16 v[16:19], v[84:87], v[188:191], v[16:19]
	v_mfma_f32_16x16x32_bf16 v[12:15], v[104:107], v[188:191], v[12:15]
	v_mfma_f32_16x16x32_bf16 v[64:67], v[88:91], v[168:171], v[64:67]
	v_mfma_f32_16x16x32_bf16 v[60:63], v[112:115], v[168:171], v[60:63]
	v_mfma_f32_16x16x32_bf16 v[48:51], v[88:91], v[176:179], v[48:51]
	v_mfma_f32_16x16x32_bf16 v[44:47], v[112:115], v[176:179], v[44:47]
	v_mfma_f32_16x16x32_bf16 v[32:35], v[88:91], v[184:187], v[32:35]
	v_mfma_f32_16x16x32_bf16 v[28:31], v[112:115], v[184:187], v[28:31]
	v_mfma_f32_16x16x32_bf16 v[16:19], v[88:91], v[192:195], v[16:19]
	v_mfma_f32_16x16x32_bf16 v[12:15], v[112:115], v[192:195], v[12:15]
	s_setprio 0
	s_setprio 1
	v_mfma_f32_16x16x32_bf16 v[56:59], v[124:127], v[164:167], v[56:59]
	v_mfma_f32_16x16x32_bf16 v[52:55], v[148:151], v[164:167], v[52:55]
	v_mfma_f32_16x16x32_bf16 v[40:43], v[124:127], v[172:175], v[40:43]
	v_mfma_f32_16x16x32_bf16 v[36:39], v[148:151], v[172:175], v[36:39]
	v_mfma_f32_16x16x32_bf16 v[24:27], v[124:127], v[180:183], v[24:27]
	v_mfma_f32_16x16x32_bf16 v[20:23], v[148:151], v[180:183], v[20:23]
	v_mfma_f32_16x16x32_bf16 v[8:11], v[124:127], v[188:191], v[8:11]
	v_mfma_f32_16x16x32_bf16 v[4:7], v[148:151], v[188:191], v[4:7]
	v_mfma_f32_16x16x32_bf16 v[56:59], v[136:139], v[168:171], v[56:59]
	v_mfma_f32_16x16x32_bf16 v[52:55], v[160:163], v[168:171], v[52:55]
	v_mfma_f32_16x16x32_bf16 v[40:43], v[136:139], v[176:179], v[40:43]
	v_mfma_f32_16x16x32_bf16 v[36:39], v[160:163], v[176:179], v[36:39]
	v_mfma_f32_16x16x32_bf16 v[24:27], v[136:139], v[184:187], v[24:27]
	v_mfma_f32_16x16x32_bf16 v[20:23], v[160:163], v[184:187], v[20:23]
	v_mfma_f32_16x16x32_bf16 v[8:11], v[136:139], v[192:195], v[8:11]
	v_mfma_f32_16x16x32_bf16 v[4:7], v[160:163], v[192:195], v[4:7]
	s_setprio 0
	s_barrier
	s_add_i32 s83, 0, 0x18000
	s_add_i32 s85, 0, 0x1c000
	v_add_u32_e32 v112, s83, v197
	v_add_u32_e32 v160, s85, v197
	ds_read_b128 v[84:87], v112
	ds_read_b128 v[88:91], v112 offset:1024
	ds_read_b128 v[104:107], v112 offset:2048
	ds_read_b128 v[112:115], v112 offset:3072
	ds_read_b128 v[124:127], v160
	ds_read_b128 v[136:139], v160 offset:1024
	ds_read_b128 v[148:151], v160 offset:2048
	ds_read_b128 v[160:163], v160 offset:3072
	s_add_u32 s54, s54, 0x80000
	s_addc_u32 s55, s55, 0
	s_mov_b32 m0, s60
	ds_read_b128 v[164:167], v231 offset:32768
	ds_read_b128 v[168:171], v231 offset:33792
	ds_read_b128 v[172:175], v231 offset:34816
	ds_read_b128 v[176:179], v231 offset:35840
	ds_read_b128 v[180:183], v231 offset:36864
	ds_read_b128 v[184:187], v231 offset:37888
	ds_read_b128 v[188:191], v231 offset:38912
	ds_read_b128 v[192:195], v231 offset:39936
	global_load_lds_dwordx4 v204, s[54:55]
	s_mov_b32 m0, s61
	s_nop 0
	global_load_lds_dwordx4 v206, s[54:55]
	s_waitcnt vmcnt(8)
	s_waitcnt lgkmcnt(0)
	s_barrier
	s_setprio 1
	s_waitcnt lgkmcnt(0)
	v_mfma_f32_16x16x32_bf16 v[156:159], v[84:87], v[164:167], v[156:159]
	v_mfma_f32_16x16x32_bf16 v[152:155], v[104:107], v[164:167], v[152:155]
	v_mfma_f32_16x16x32_bf16 v[132:135], v[84:87], v[172:175], v[132:135]
	v_mfma_f32_16x16x32_bf16 v[128:131], v[104:107], v[172:175], v[128:131]
	v_mfma_f32_16x16x32_bf16 v[108:111], v[84:87], v[180:183], v[108:111]
	v_mfma_f32_16x16x32_bf16 v[100:103], v[104:107], v[180:183], v[100:103]
	v_mfma_f32_16x16x32_bf16 v[80:83], v[84:87], v[188:191], v[80:83]
	v_mfma_f32_16x16x32_bf16 v[76:79], v[104:107], v[188:191], v[76:79]
	v_mfma_f32_16x16x32_bf16 v[156:159], v[88:91], v[168:171], v[156:159]
	v_mfma_f32_16x16x32_bf16 v[152:155], v[112:115], v[168:171], v[152:155]
	v_mfma_f32_16x16x32_bf16 v[132:135], v[88:91], v[176:179], v[132:135]
	v_mfma_f32_16x16x32_bf16 v[128:131], v[112:115], v[176:179], v[128:131]
	v_mfma_f32_16x16x32_bf16 v[108:111], v[88:91], v[184:187], v[108:111]
	v_mfma_f32_16x16x32_bf16 v[100:103], v[112:115], v[184:187], v[100:103]
	v_mfma_f32_16x16x32_bf16 v[80:83], v[88:91], v[192:195], v[80:83]
	v_mfma_f32_16x16x32_bf16 v[76:79], v[112:115], v[192:195], v[76:79]
	s_setprio 0
	s_setprio 1
	v_mfma_f32_16x16x32_bf16 v[144:147], v[124:127], v[164:167], v[144:147]
	v_mfma_f32_16x16x32_bf16 v[140:143], v[148:151], v[164:167], v[140:143]
	v_mfma_f32_16x16x32_bf16 v[120:123], v[124:127], v[172:175], v[120:123]
	v_mfma_f32_16x16x32_bf16 v[116:119], v[148:151], v[172:175], v[116:119]
	v_mfma_f32_16x16x32_bf16 v[96:99], v[124:127], v[180:183], v[96:99]
	v_mfma_f32_16x16x32_bf16 v[92:95], v[148:151], v[180:183], v[92:95]
	v_mfma_f32_16x16x32_bf16 v[72:75], v[124:127], v[188:191], v[72:75]
	v_mfma_f32_16x16x32_bf16 v[68:71], v[148:151], v[188:191], v[68:71]
	v_mfma_f32_16x16x32_bf16 v[144:147], v[136:139], v[168:171], v[144:147]
	v_mfma_f32_16x16x32_bf16 v[140:143], v[160:163], v[168:171], v[140:143]
	v_mfma_f32_16x16x32_bf16 v[120:123], v[136:139], v[176:179], v[120:123]
	v_mfma_f32_16x16x32_bf16 v[116:119], v[160:163], v[176:179], v[116:119]
	v_mfma_f32_16x16x32_bf16 v[96:99], v[136:139], v[184:187], v[96:99]
	v_mfma_f32_16x16x32_bf16 v[92:95], v[160:163], v[184:187], v[92:95]
	v_mfma_f32_16x16x32_bf16 v[72:75], v[136:139], v[192:195], v[72:75]
	v_mfma_f32_16x16x32_bf16 v[68:71], v[160:163], v[192:195], v[68:71]
	s_setprio 0
	s_barrier
; #define PG8_STAGE(bufoff, gbase, voff) do { _Pragma("unroll") for (int _i = 0; _i < 2; ++_i) \
;         __builtin_amdgcn_global_load_lds((const unsigned*)((const char*)(gbase) + (voff)[_i]), (LAS unsigned*)(lds + (bufoff) + ldsw + _i * 8192), 16, 0, 0); } while (0)
; #define PG8_LDA(dst, b, h) do { _Pragma("unroll") for (int m = 0; m < 4; ++m) _Pragma("unroll") for (int k = 0; k < 2; ++k) dst[m][k] = *(const LAS bf16x8*)(lds + PG8_SA(b, h) + aoff + m * 2048 + k * 1024); } while (0)
; #define PG8_MMA(ai, bj, At, Bt) do { __builtin_amdgcn_s_setprio(1); _Pragma("unroll") for (int m = 0; m < 4; ++m) _Pragma("unroll") for (int n = 0; n < 2; ++n) _Pragma("unroll") for (int k = 0; k < 2; ++k) \
;         acc[ai][bj][m][n] = __builtin_amdgcn_mfma_f32_16x16x32_bf16(Bt[n][k], At[m][k], acc[ai][bj][m][n], 0, 0, 0); __builtin_amdgcn_s_setprio(0); } while (0)
; #define PG8_WAIT_V(n) asm volatile("s_waitcnt vmcnt(" #n ")" ::: "memory")
; #define PG8_WAIT_L(n) asm volatile("s_waitcnt lgkmcnt(" #n ")" ::: "memory")
; #define PG8_BAR __builtin_amdgcn_s_barrier()
; #define PG8_SCHED __builtin_amdgcn_sched_barrier(0)
; template <class Epi, class Sched>
; DI void gemm_phase(LAS unsigned char* lds, const Sched& S, const Epi& E) {
;     ...
;             PG8_LDA(At, 1, 1); PG8_STAGE(PG8_SB(1, 0), b3, voffB); PG8_STAGE(PG8_SB(1, 1), b3 + hstepB, voffB); PG8_STAGE(PG8_SA(1, 0), a3, voffA);
;             PG8_WAIT_V(8); PG8_WAIT_L(0); PG8_BAR; PG8_MMA(1, 0, At, B0); PG8_MMA(1, 1, At, B1); PG8_BAR; PG8_SCHED;
;         }
	s_add_i32 s54, s83, s23
	s_add_u32 s52, s52, 0x80
	s_addc_u32 s53, s53, 0
	s_mov_b32 m0, s54
	ds_read_b128 v[164:167], v231 offset:49152
	ds_read_b128 v[168:171], v231 offset:50176
	ds_read_b128 v[172:175], v231 offset:51200
	ds_read_b128 v[176:179], v231 offset:52224
	ds_read_b128 v[180:183], v231 offset:53248
	ds_read_b128 v[184:187], v231 offset:54272
	ds_read_b128 v[188:191], v231 offset:55296
	ds_read_b128 v[192:195], v231 offset:56320
	global_load_lds_dwordx4 v2, s[52:53]
	s_add_i32 m0, s54, 0x2000
	s_add_i32 s54, s85, s23
	global_load_lds_dwordx4 v208, s[52:53]
	s_add_u32 s52, s52, 0x80000
	s_addc_u32 s53, s53, 0
	s_mov_b32 m0, s54
	s_nop 0
	global_load_lds_dwordx4 v2, s[52:53]
	s_add_i32 m0, s54, 0x2000
	s_nop 0
	global_load_lds_dwordx4 v208, s[52:53]
	s_mov_b32 m0, s71
	s_nop 0
	global_load_lds_dwordx4 v204, s[98:99]
	s_mov_b32 m0, s72
	s_nop 0
	global_load_lds_dwordx4 v206, s[98:99]
	s_waitcnt vmcnt(8)
	s_waitcnt lgkmcnt(0)
	s_barrier
	s_setprio 1
	s_waitcnt lgkmcnt(0)
	v_mfma_f32_16x16x32_bf16 v[64:67], v[84:87], v[164:167], v[64:67]
	v_mfma_f32_16x16x32_bf16 v[60:63], v[104:107], v[164:167], v[60:63]
	v_mfma_f32_16x16x32_bf16 v[48:51], v[84:87], v[172:175], v[48:51]
	v_mfma_f32_16x16x32_bf16 v[44:47], v[104:107], v[172:175], v[44:47]
	v_mfma_f32_16x16x32_bf16 v[32:35], v[84:87], v[180:183], v[32:35]
	v_mfma_f32_16x16x32_bf16 v[28:31], v[104:107], v[180:183], v[28:31]
	v_mfma_f32_16x16x32_bf16 v[16:19], v[84:87], v[188:191], v[16:19]
	v_mfma_f32_16x16x32_bf16 v[12:15], v[104:107], v[188:191], v[12:15]
	v_mfma_f32_16x16x32_bf16 v[64:67], v[88:91], v[168:171], v[64:67]
	v_mfma_f32_16x16x32_bf16 v[60:63], v[112:115], v[168:171], v[60:63]
	v_mfma_f32_16x16x32_bf16 v[48:51], v[88:91], v[176:179], v[48:51]
	v_mfma_f32_16x16x32_bf16 v[44:47], v[112:115], v[176:179], v[44:47]
	v_mfma_f32_16x16x32_bf16 v[32:35], v[88:91], v[184:187], v[32:35]
	v_mfma_f32_16x16x32_bf16 v[28:31], v[112:115], v[184:187], v[28:31]
	v_mfma_f32_16x16x32_bf16 v[16:19], v[88:91], v[192:195], v[16:19]
	v_mfma_f32_16x16x32_bf16 v[12:15], v[112:115], v[192:195], v[12:15]
	s_setprio 0
	s_setprio 1
	v_mfma_f32_16x16x32_bf16 v[56:59], v[124:127], v[164:167], v[56:59]
	v_mfma_f32_16x16x32_bf16 v[52:55], v[148:151], v[164:167], v[52:55]
	v_mfma_f32_16x16x32_bf16 v[40:43], v[124:127], v[172:175], v[40:43]
	v_mfma_f32_16x16x32_bf16 v[36:39], v[148:151], v[172:175], v[36:39]
	v_mfma_f32_16x16x32_bf16 v[24:27], v[124:127], v[180:183], v[24:27]
	v_mfma_f32_16x16x32_bf16 v[20:23], v[148:151], v[180:183], v[20:23]
	v_mfma_f32_16x16x32_bf16 v[8:11], v[124:127], v[188:191], v[8:11]
	v_mfma_f32_16x16x32_bf16 v[4:7], v[148:151], v[188:191], v[4:7]
	v_mfma_f32_16x16x32_bf16 v[56:59], v[136:139], v[168:171], v[56:59]
	v_mfma_f32_16x16x32_bf16 v[52:55], v[160:163], v[168:171], v[52:55]
	v_mfma_f32_16x16x32_bf16 v[40:43], v[136:139], v[176:179], v[40:43]
	v_mfma_f32_16x16x32_bf16 v[36:39], v[160:163], v[176:179], v[36:39]
	v_mfma_f32_16x16x32_bf16 v[24:27], v[136:139], v[184:187], v[24:27]
	v_mfma_f32_16x16x32_bf16 v[20:23], v[160:163], v[184:187], v[20:23]
	v_mfma_f32_16x16x32_bf16 v[8:11], v[136:139], v[192:195], v[8:11]
	v_mfma_f32_16x16x32_bf16 v[4:7], v[160:163], v[192:195], v[4:7]
	s_setprio 0
	s_barrier
	s_add_u32 s80, s80, 0x100
	s_addc_u32 s81, s81, 0
	s_add_u32 s42, s42, 0x100
	s_addc_u32 s43, s43, 0
	s_cmp_ge_i32 s82, s75
	s_mov_b32 s52, s82
	s_cbranch_scc0 .LBB0_1104
	s_and_b64 vcc, exec, s[38:39]
	s_cbranch_vccz .LBB0_1107
	s_barrier

; #define PG8_STAGE(bufoff, gbase, voff) do { _Pragma("unroll") for (int _i = 0; _i < 2; ++_i) \
;         __builtin_amdgcn_global_load_lds((const unsigned*)((const char*)(gbase) + (voff)[_i]), (LAS unsigned*)(lds + (bufoff) + ldsw + _i * 8192), 16, 0, 0); } while (0)
; #define PG8_LDA(dst, b, h) do { _Pragma("unroll") for (int m = 0; m < 4; ++m) _Pragma("unroll") for (int k = 0; k < 2; ++k) dst[m][k] = *(const LAS bf16x8*)(lds + PG8_SA(b, h) + aoff + m * 2048 + k * 1024); } while (0)
; #define PG8_LDB(dst, b, h) do { _Pragma("unroll") for (int n = 0; n < 2; ++n) _Pragma("unroll") for (int k = 0; k < 2; ++k) dst[n][k] = *(const LAS bf16x8*)(lds + PG8_SB(b, h) + boff + n * 2048 + k * 1024); } while (0)
; #define PG8_MMA(ai, bj, At, Bt) do { __builtin_amdgcn_s_setprio(1); _Pragma("unroll") for (int m = 0; m < 4; ++m) _Pragma("unroll") for (int n = 0; n < 2; ++n) _Pragma("unroll") for (int k = 0; k < 2; ++k) \
;         acc[ai][bj][m][n] = __builtin_amdgcn_mfma_f32_16x16x32_bf16(Bt[n][k], At[m][k], acc[ai][bj][m][n], 0, 0, 0); __builtin_amdgcn_s_setprio(0); } while (0)
; #define PG8_WAIT_V(n) asm volatile("s_waitcnt vmcnt(" #n ")" ::: "memory")
; #define PG8_WAIT_L(n) asm volatile("s_waitcnt lgkmcnt(" #n ")" ::: "memory")
; #define PG8_BAR __builtin_amdgcn_s_barrier()
; template <class Epi, class Sched>
; DI void gemm_phase(LAS unsigned char* lds, const Sched& S, const Epi& E) {
;     ...
;             const bool last = (t == nt - 2);
;             const char* a1 = cA + (size_t)(t + 1) * kstep;
;             const char* a2 = last ? nA : cA + (size_t)(t + 2) * kstep; const char* b2 = last ? nB : cB + (size_t)(t + 2) * kstep;
;             const char* a3 = a2 + kstep; const char* b3 = b2 + kstep;
;             if constexpr (Epi::HOOK) { if (cur.ks < 0 && (t == 16 || t == 32)) E.hook(acc, cur, t >> 4, wr, wc, fr, fq); }
;             PG8_LDB(B0, 0, 0); PG8_LDB(B1, 0, 1); PG8_SCHED; PG8_LDA(At, 0, 0); PG8_STAGE(PG8_SA(1, 1), a1 + hstepA, voffA);
;             PG8_WAIT_V(8); PG8_WAIT_L(0); PG8_BAR; PG8_MMA(0, 0, At, B0); PG8_MMA(0, 1, At, B1); PG8_BAR; PG8_SCHED;
;             PG8_LDA(At, 0, 1); PG8_STAGE(PG8_SB(0, 0), b2, voffB); PG8_STAGE(PG8_SB(0, 1), b2 + hstepB, voffB); PG8_STAGE(PG8_SA(0, 0), a2, voffA);
;             PG8_WAIT_V(8); PG8_WAIT_L(0); PG8_BAR; PG8_MMA(1, 0, At, B0); PG8_MMA(1, 1, At, B1); PG8_BAR; PG8_SCHED;
.LBB0_1184:
	s_add_i32 s85, s54, 2
	s_add_u32 s55, s42, 0xfff80080
	s_addc_u32 s56, s43, -1
	s_add_i32 s86, 0, 0x10000
	s_cmp_eq_u32 s81, s54
	s_cselect_b32 s57, s58, s56
	s_cselect_b32 s56, s59, s55
	v_add_u32_e32 v149, s86, v146
	s_cselect_b32 s55, s60, s83
	s_cselect_b32 s54, s61, s82
	s_add_i32 s88, 0, 0x14000
	ds_read_b128 v[142:145], v149
	ds_read_b128 v[150:153], v149 offset:1024
	ds_read_b128 v[154:157], v149 offset:2048
	ds_read_b128 v[158:161], v149 offset:3072
	v_add_u32_e32 v149, s88, v146
	ds_read_b128 v[162:165], v149
	ds_read_b128 v[166:169], v149 offset:1024
	ds_read_b128 v[170:173], v149 offset:2048
	ds_read_b128 v[174:177], v149 offset:3072
	s_add_i32 m0, s26, 0xc000
	ds_read_b128 v[178:181], v148
	ds_read_b128 v[182:185], v148 offset:1024
	ds_read_b128 v[186:189], v148 offset:2048
	ds_read_b128 v[190:193], v148 offset:3072
	ds_read_b128 v[204:207], v148 offset:4096
	ds_read_b128 v[208:211], v148 offset:5120
	ds_read_b128 v[212:215], v148 offset:6144
	ds_read_b128 v[230:233], v148 offset:7168
	global_load_lds_dwordx4 v140, s[42:43]
	s_add_i32 m0, s26, 0xe000
	s_nop 0
	global_load_lds_dwordx4 v138, s[42:43]
	s_waitcnt vmcnt(8)
	s_waitcnt lgkmcnt(0)
	s_barrier
	s_setprio 1
	s_waitcnt lgkmcnt(0)
	v_mfma_f32_16x16x32_bf16 v[128:131], v[142:145], v[178:181], v[128:131]
	v_mfma_f32_16x16x32_bf16 v[124:127], v[154:157], v[178:181], v[124:127]
	v_mfma_f32_16x16x32_bf16 v[112:115], v[142:145], v[186:189], v[112:115]
	v_mfma_f32_16x16x32_bf16 v[108:111], v[154:157], v[186:189], v[108:111]
	v_mfma_f32_16x16x32_bf16 v[96:99], v[142:145], v[204:207], v[96:99]
	v_mfma_f32_16x16x32_bf16 v[92:95], v[154:157], v[204:207], v[92:95]
	v_mfma_f32_16x16x32_bf16 v[80:83], v[142:145], v[212:215], v[80:83]
	v_mfma_f32_16x16x32_bf16 v[76:79], v[154:157], v[212:215], v[76:79]
	v_mfma_f32_16x16x32_bf16 v[128:131], v[150:153], v[182:185], v[128:131]
	v_mfma_f32_16x16x32_bf16 v[124:127], v[158:161], v[182:185], v[124:127]
	v_mfma_f32_16x16x32_bf16 v[112:115], v[150:153], v[190:193], v[112:115]
	v_mfma_f32_16x16x32_bf16 v[108:111], v[158:161], v[190:193], v[108:111]
	v_mfma_f32_16x16x32_bf16 v[96:99], v[150:153], v[208:211], v[96:99]
	v_mfma_f32_16x16x32_bf16 v[92:95], v[158:161], v[208:211], v[92:95]
	v_mfma_f32_16x16x32_bf16 v[80:83], v[150:153], v[230:233], v[80:83]
	v_mfma_f32_16x16x32_bf16 v[76:79], v[158:161], v[230:233], v[76:79]
	s_setprio 0
	s_setprio 1
	v_mfma_f32_16x16x32_bf16 v[120:123], v[162:165], v[178:181], v[120:123]
	v_mfma_f32_16x16x32_bf16 v[116:119], v[170:173], v[178:181], v[116:119]
	v_mfma_f32_16x16x32_bf16 v[104:107], v[162:165], v[186:189], v[104:107]
	v_mfma_f32_16x16x32_bf16 v[100:103], v[170:173], v[186:189], v[100:103]
	v_mfma_f32_16x16x32_bf16 v[88:91], v[162:165], v[204:207], v[88:91]
	v_mfma_f32_16x16x32_bf16 v[84:87], v[170:173], v[204:207], v[84:87]
	v_mfma_f32_16x16x32_bf16 v[72:75], v[162:165], v[212:215], v[72:75]
	v_mfma_f32_16x16x32_bf16 v[68:71], v[170:173], v[212:215], v[68:71]
	v_mfma_f32_16x16x32_bf16 v[120:123], v[166:169], v[182:185], v[120:123]
	v_mfma_f32_16x16x32_bf16 v[116:119], v[174:177], v[182:185], v[116:119]
	v_mfma_f32_16x16x32_bf16 v[104:107], v[166:169], v[190:193], v[104:107]
	v_mfma_f32_16x16x32_bf16 v[100:103], v[174:177], v[190:193], v[100:103]
	v_mfma_f32_16x16x32_bf16 v[88:91], v[166:169], v[208:211], v[88:91]
	v_mfma_f32_16x16x32_bf16 v[84:87], v[174:177], v[208:211], v[84:87]
	v_mfma_f32_16x16x32_bf16 v[72:75], v[166:169], v[230:233], v[72:75]
	v_mfma_f32_16x16x32_bf16 v[68:71], v[174:177], v[230:233], v[68:71]
	s_setprio 0
	s_barrier
	s_add_i32 s86, s86, s23
	s_mov_b32 m0, s86
	ds_read_b128 v[178:181], v148 offset:16384
	ds_read_b128 v[182:185], v148 offset:17408
	ds_read_b128 v[186:189], v148 offset:18432
	ds_read_b128 v[190:193], v148 offset:19456
	ds_read_b128 v[204:207], v148 offset:20480
	ds_read_b128 v[208:211], v148 offset:21504
	ds_read_b128 v[212:215], v148 offset:22528
	ds_read_b128 v[230:233], v148 offset:23552
	global_load_lds_dwordx4 v2, s[54:55]
	s_add_i32 m0, s86, 0x2000
	s_add_u32 s86, s54, 0x80000
	s_addc_u32 s87, s55, 0
	s_add_i32 s88, s88, s23
	global_load_lds_dwordx4 v136, s[54:55]
	s_mov_b32 m0, s88
	s_nop 0
	global_load_lds_dwordx4 v2, s[86:87]
	s_add_i32 m0, s88, 0x2000
	s_nop 0
	global_load_lds_dwordx4 v136, s[86:87]
	s_add_u32 s98, s56, 0x80
	s_addc_u32 s99, s57, 0
	s_mov_b32 m0, s26
	s_nop 0
	global_load_lds_dwordx4 v132, s[56:57]
	s_mov_b32 m0, s27
	s_nop 0
	global_load_lds_dwordx4 v134, s[56:57]
	s_waitcnt vmcnt(8)
	s_waitcnt lgkmcnt(0)
	s_barrier
; #define PG8_STAGE(bufoff, gbase, voff) do { _Pragma("unroll") for (int _i = 0; _i < 2; ++_i) \
;         __builtin_amdgcn_global_load_lds((const unsigned*)((const char*)(gbase) + (voff)[_i]), (LAS unsigned*)(lds + (bufoff) + ldsw + _i * 8192), 16, 0, 0); } while (0)
; #define PG8_LDA(dst, b, h) do { _Pragma("unroll") for (int m = 0; m < 4; ++m) _Pragma("unroll") for (int k = 0; k < 2; ++k) dst[m][k] = *(const LAS bf16x8*)(lds + PG8_SA(b, h) + aoff + m * 2048 + k * 1024); } while (0)
; #define PG8_LDB(dst, b, h) do { _Pragma("unroll") for (int n = 0; n < 2; ++n) _Pragma("unroll") for (int k = 0; k < 2; ++k) dst[n][k] = *(const LAS bf16x8*)(lds + PG8_SB(b, h) + boff + n * 2048 + k * 1024); } while (0)
; #define PG8_MMA(ai, bj, At, Bt) do { __builtin_amdgcn_s_setprio(1); _Pragma("unroll") for (int m = 0; m < 4; ++m) _Pragma("unroll") for (int n = 0; n < 2; ++n) _Pragma("unroll") for (int k = 0; k < 2; ++k) \
;         acc[ai][bj][m][n] = __builtin_amdgcn_mfma_f32_16x16x32_bf16(Bt[n][k], At[m][k], acc[ai][bj][m][n], 0, 0, 0); __builtin_amdgcn_s_setprio(0); } while (0)
; #define PG8_WAIT_V(n) asm volatile("s_waitcnt vmcnt(" #n ")" ::: "memory")
; #define PG8_WAIT_L(n) asm volatile("s_waitcnt lgkmcnt(" #n ")" ::: "memory")
; #define PG8_BAR __builtin_amdgcn_s_barrier()
; #define PG8_SCHED __builtin_amdgcn_sched_barrier(0)
; template <class Epi, class Sched>
; DI void gemm_phase(LAS unsigned char* lds, const Sched& S, const Epi& E) {
;     ...
;             PG8_WAIT_V(8); PG8_WAIT_L(0); PG8_BAR; PG8_MMA(1, 0, At, B0); PG8_MMA(1, 1, At, B1); PG8_BAR; PG8_SCHED;
;             PG8_LDB(B0, 1, 0); PG8_LDB(B1, 1, 1); PG8_SCHED; PG8_LDA(At, 1, 0); PG8_STAGE(PG8_SA(0, 1), a2 + hstepA, voffA);
;             PG8_WAIT_V(8); PG8_WAIT_L(0); PG8_BAR; PG8_MMA(0, 0, At, B0); PG8_MMA(0, 1, At, B1); PG8_BAR; PG8_SCHED;
	s_setprio 1
	s_waitcnt lgkmcnt(0)
	v_mfma_f32_16x16x32_bf16 v[64:67], v[142:145], v[178:181], v[64:67]
	v_mfma_f32_16x16x32_bf16 v[60:63], v[154:157], v[178:181], v[60:63]
	v_mfma_f32_16x16x32_bf16 v[48:51], v[142:145], v[186:189], v[48:51]
	v_mfma_f32_16x16x32_bf16 v[44:47], v[154:157], v[186:189], v[44:47]
	v_mfma_f32_16x16x32_bf16 v[32:35], v[142:145], v[204:207], v[32:35]
	v_mfma_f32_16x16x32_bf16 v[28:31], v[154:157], v[204:207], v[28:31]
	v_mfma_f32_16x16x32_bf16 v[16:19], v[142:145], v[212:215], v[16:19]
	v_mfma_f32_16x16x32_bf16 v[12:15], v[154:157], v[212:215], v[12:15]
	v_mfma_f32_16x16x32_bf16 v[64:67], v[150:153], v[182:185], v[64:67]
	v_mfma_f32_16x16x32_bf16 v[60:63], v[158:161], v[182:185], v[60:63]
	v_mfma_f32_16x16x32_bf16 v[48:51], v[150:153], v[190:193], v[48:51]
	v_mfma_f32_16x16x32_bf16 v[44:47], v[158:161], v[190:193], v[44:47]
	v_mfma_f32_16x16x32_bf16 v[32:35], v[150:153], v[208:211], v[32:35]
	v_mfma_f32_16x16x32_bf16 v[28:31], v[158:161], v[208:211], v[28:31]
	v_mfma_f32_16x16x32_bf16 v[16:19], v[150:153], v[230:233], v[16:19]
	v_mfma_f32_16x16x32_bf16 v[12:15], v[158:161], v[230:233], v[12:15]
	s_setprio 0
	s_setprio 1
	v_mfma_f32_16x16x32_bf16 v[56:59], v[162:165], v[178:181], v[56:59]
	v_mfma_f32_16x16x32_bf16 v[52:55], v[170:173], v[178:181], v[52:55]
	v_mfma_f32_16x16x32_bf16 v[40:43], v[162:165], v[186:189], v[40:43]
	v_mfma_f32_16x16x32_bf16 v[36:39], v[170:173], v[186:189], v[36:39]
	v_mfma_f32_16x16x32_bf16 v[24:27], v[162:165], v[204:207], v[24:27]
	v_mfma_f32_16x16x32_bf16 v[20:23], v[170:173], v[204:207], v[20:23]
	v_mfma_f32_16x16x32_bf16 v[8:11], v[162:165], v[212:215], v[8:11]
	v_mfma_f32_16x16x32_bf16 v[4:7], v[170:173], v[212:215], v[4:7]
	v_mfma_f32_16x16x32_bf16 v[56:59], v[166:169], v[182:185], v[56:59]
	v_mfma_f32_16x16x32_bf16 v[52:55], v[174:177], v[182:185], v[52:55]
	v_mfma_f32_16x16x32_bf16 v[40:43], v[166:169], v[190:193], v[40:43]
	v_mfma_f32_16x16x32_bf16 v[36:39], v[174:177], v[190:193], v[36:39]
	v_mfma_f32_16x16x32_bf16 v[24:27], v[166:169], v[208:211], v[24:27]
	v_mfma_f32_16x16x32_bf16 v[20:23], v[174:177], v[208:211], v[20:23]
	v_mfma_f32_16x16x32_bf16 v[8:11], v[166:169], v[230:233], v[8:11]
	v_mfma_f32_16x16x32_bf16 v[4:7], v[174:177], v[230:233], v[4:7]
	s_setprio 0
	s_barrier
	s_add_i32 s86, 0, 0x18000
	v_add_u32_e32 v149, s86, v146
	s_add_i32 s87, 0, 0x1c000
	ds_read_b128 v[142:145], v149
	ds_read_b128 v[150:153], v149 offset:1024
	ds_read_b128 v[154:157], v149 offset:2048
	ds_read_b128 v[158:161], v149 offset:3072
	v_add_u32_e32 v149, s87, v146
	ds_read_b128 v[162:165], v149
	ds_read_b128 v[166:169], v149 offset:1024
	ds_read_b128 v[170:173], v149 offset:2048
	ds_read_b128 v[174:177], v149 offset:3072
	s_add_u32 s56, s56, 0x80000
	s_addc_u32 s57, s57, 0
	s_mov_b32 m0, s65
	ds_read_b128 v[178:181], v148 offset:32768
	ds_read_b128 v[182:185], v148 offset:33792
	ds_read_b128 v[186:189], v148 offset:34816
	ds_read_b128 v[190:193], v148 offset:35840
	ds_read_b128 v[204:207], v148 offset:36864
	ds_read_b128 v[208:211], v148 offset:37888
	ds_read_b128 v[212:215], v148 offset:38912
	ds_read_b128 v[230:233], v148 offset:39936
	global_load_lds_dwordx4 v132, s[56:57]
	s_mov_b32 m0, s66
	s_nop 0
	global_load_lds_dwordx4 v134, s[56:57]
	s_waitcnt vmcnt(8)
	s_waitcnt lgkmcnt(0)
	s_barrier
	s_setprio 1
	s_waitcnt lgkmcnt(0)
	v_mfma_f32_16x16x32_bf16 v[128:131], v[142:145], v[178:181], v[128:131]
	v_mfma_f32_16x16x32_bf16 v[124:127], v[154:157], v[178:181], v[124:127]
	v_mfma_f32_16x16x32_bf16 v[112:115], v[142:145], v[186:189], v[112:115]
	v_mfma_f32_16x16x32_bf16 v[108:111], v[154:157], v[186:189], v[108:111]
	v_mfma_f32_16x16x32_bf16 v[96:99], v[142:145], v[204:207], v[96:99]
	v_mfma_f32_16x16x32_bf16 v[92:95], v[154:157], v[204:207], v[92:95]
	v_mfma_f32_16x16x32_bf16 v[80:83], v[142:145], v[212:215], v[80:83]
	v_mfma_f32_16x16x32_bf16 v[76:79], v[154:157], v[212:215], v[76:79]
	v_mfma_f32_16x16x32_bf16 v[128:131], v[150:153], v[182:185], v[128:131]
	v_mfma_f32_16x16x32_bf16 v[124:127], v[158:161], v[182:185], v[124:127]
	v_mfma_f32_16x16x32_bf16 v[112:115], v[150:153], v[190:193], v[112:115]
	v_mfma_f32_16x16x32_bf16 v[108:111], v[158:161], v[190:193], v[108:111]
	v_mfma_f32_16x16x32_bf16 v[96:99], v[150:153], v[208:211], v[96:99]
	v_mfma_f32_16x16x32_bf16 v[92:95], v[158:161], v[208:211], v[92:95]
	v_mfma_f32_16x16x32_bf16 v[80:83], v[150:153], v[230:233], v[80:83]
	v_mfma_f32_16x16x32_bf16 v[76:79], v[158:161], v[230:233], v[76:79]
	s_setprio 0
	s_setprio 1
	v_mfma_f32_16x16x32_bf16 v[120:123], v[162:165], v[178:181], v[120:123]
	v_mfma_f32_16x16x32_bf16 v[116:119], v[170:173], v[178:181], v[116:119]
	v_mfma_f32_16x16x32_bf16 v[104:107], v[162:165], v[186:189], v[104:107]
	v_mfma_f32_16x16x32_bf16 v[100:103], v[170:173], v[186:189], v[100:103]
	v_mfma_f32_16x16x32_bf16 v[88:91], v[162:165], v[204:207], v[88:91]
	v_mfma_f32_16x16x32_bf16 v[84:87], v[170:173], v[204:207], v[84:87]
	v_mfma_f32_16x16x32_bf16 v[72:75], v[162:165], v[212:215], v[72:75]
	v_mfma_f32_16x16x32_bf16 v[68:71], v[170:173], v[212:215], v[68:71]
	v_mfma_f32_16x16x32_bf16 v[120:123], v[166:169], v[182:185], v[120:123]
	v_mfma_f32_16x16x32_bf16 v[116:119], v[174:177], v[182:185], v[116:119]
	v_mfma_f32_16x16x32_bf16 v[104:107], v[166:169], v[190:193], v[104:107]
	v_mfma_f32_16x16x32_bf16 v[100:103], v[174:177], v[190:193], v[100:103]
	v_mfma_f32_16x16x32_bf16 v[88:91], v[166:169], v[208:211], v[88:91]
	v_mfma_f32_16x16x32_bf16 v[84:87], v[174:177], v[208:211], v[84:87]
	v_mfma_f32_16x16x32_bf16 v[72:75], v[166:169], v[230:233], v[72:75]
	v_mfma_f32_16x16x32_bf16 v[68:71], v[174:177], v[230:233], v[68:71]
	s_setprio 0
	s_barrier
; #define PG8_STAGE(bufoff, gbase, voff) do { _Pragma("unroll") for (int _i = 0; _i < 2; ++_i) \
;         __builtin_amdgcn_global_load_lds((const unsigned*)((const char*)(gbase) + (voff)[_i]), (LAS unsigned*)(lds + (bufoff) + ldsw + _i * 8192), 16, 0, 0); } while (0)
; #define PG8_LDA(dst, b, h) do { _Pragma("unroll") for (int m = 0; m < 4; ++m) _Pragma("unroll") for (int k = 0; k < 2; ++k) dst[m][k] = *(const LAS bf16x8*)(lds + PG8_SA(b, h) + aoff + m * 2048 + k * 1024); } while (0)
; #define PG8_MMA(ai, bj, At, Bt) do { __builtin_amdgcn_s_setprio(1); _Pragma("unroll") for (int m = 0; m < 4; ++m) _Pragma("unroll") for (int n = 0; n < 2; ++n) _Pragma("unroll") for (int k = 0; k < 2; ++k) \
;         acc[ai][bj][m][n] = __builtin_amdgcn_mfma_f32_16x16x32_bf16(Bt[n][k], At[m][k], acc[ai][bj][m][n], 0, 0, 0); __builtin_amdgcn_s_setprio(0); } while (0)
; #define PG8_WAIT_V(n) asm volatile("s_waitcnt vmcnt(" #n ")" ::: "memory")
; #define PG8_WAIT_L(n) asm volatile("s_waitcnt lgkmcnt(" #n ")" ::: "memory")
; #define PG8_BAR __builtin_amdgcn_s_barrier()
; #define PG8_SCHED __builtin_amdgcn_sched_barrier(0)
; template <class Epi, class Sched>
; DI void gemm_phase(LAS unsigned char* lds, const Sched& S, const Epi& E) {
;     ...
;             PG8_LDA(At, 1, 1); PG8_STAGE(PG8_SB(1, 0), b3, voffB); PG8_STAGE(PG8_SB(1, 1), b3 + hstepB, voffB); PG8_STAGE(PG8_SA(1, 0), a3, voffA);
;             PG8_WAIT_V(8); PG8_WAIT_L(0); PG8_BAR; PG8_MMA(1, 0, At, B0); PG8_MMA(1, 1, At, B1); PG8_BAR; PG8_SCHED;
;         }
	s_add_i32 s56, s86, s23
	s_add_u32 s54, s54, 0x80
	s_addc_u32 s55, s55, 0
	s_mov_b32 m0, s56
	ds_read_b128 v[178:181], v148 offset:49152
	ds_read_b128 v[182:185], v148 offset:50176
	ds_read_b128 v[186:189], v148 offset:51200
	ds_read_b128 v[190:193], v148 offset:52224
	ds_read_b128 v[204:207], v148 offset:53248
	ds_read_b128 v[208:211], v148 offset:54272
	ds_read_b128 v[212:215], v148 offset:55296
	ds_read_b128 v[230:233], v148 offset:56320
	global_load_lds_dwordx4 v2, s[54:55]
	s_add_i32 m0, s56, 0x2000
	s_add_i32 s56, s87, s23
	global_load_lds_dwordx4 v136, s[54:55]
	s_add_u32 s54, s54, 0x80000
	s_addc_u32 s55, s55, 0
	s_mov_b32 m0, s56
	s_nop 0
	global_load_lds_dwordx4 v2, s[54:55]
	s_add_i32 m0, s56, 0x2000
	s_nop 0
	global_load_lds_dwordx4 v136, s[54:55]
	s_mov_b32 m0, s73
	s_nop 0
	global_load_lds_dwordx4 v132, s[98:99]
	s_mov_b32 m0, s74
	s_nop 0
	global_load_lds_dwordx4 v134, s[98:99]
	s_waitcnt vmcnt(8)
	s_waitcnt lgkmcnt(0)
	s_barrier
	s_setprio 1
	s_waitcnt lgkmcnt(0)
	v_mfma_f32_16x16x32_bf16 v[64:67], v[142:145], v[178:181], v[64:67]
	v_mfma_f32_16x16x32_bf16 v[60:63], v[154:157], v[178:181], v[60:63]
	v_mfma_f32_16x16x32_bf16 v[48:51], v[142:145], v[186:189], v[48:51]
	v_mfma_f32_16x16x32_bf16 v[44:47], v[154:157], v[186:189], v[44:47]
	v_mfma_f32_16x16x32_bf16 v[32:35], v[142:145], v[204:207], v[32:35]
	v_mfma_f32_16x16x32_bf16 v[28:31], v[154:157], v[204:207], v[28:31]
	v_mfma_f32_16x16x32_bf16 v[16:19], v[142:145], v[212:215], v[16:19]
	v_mfma_f32_16x16x32_bf16 v[12:15], v[154:157], v[212:215], v[12:15]
	v_mfma_f32_16x16x32_bf16 v[64:67], v[150:153], v[182:185], v[64:67]
	v_mfma_f32_16x16x32_bf16 v[60:63], v[158:161], v[182:185], v[60:63]
	v_mfma_f32_16x16x32_bf16 v[48:51], v[150:153], v[190:193], v[48:51]
	v_mfma_f32_16x16x32_bf16 v[44:47], v[158:161], v[190:193], v[44:47]
	v_mfma_f32_16x16x32_bf16 v[32:35], v[150:153], v[208:211], v[32:35]
	v_mfma_f32_16x16x32_bf16 v[28:31], v[158:161], v[208:211], v[28:31]
	v_mfma_f32_16x16x32_bf16 v[16:19], v[150:153], v[230:233], v[16:19]
	v_mfma_f32_16x16x32_bf16 v[12:15], v[158:161], v[230:233], v[12:15]
	s_setprio 0
	s_setprio 1
	v_mfma_f32_16x16x32_bf16 v[56:59], v[162:165], v[178:181], v[56:59]
	v_mfma_f32_16x16x32_bf16 v[52:55], v[170:173], v[178:181], v[52:55]
	v_mfma_f32_16x16x32_bf16 v[40:43], v[162:165], v[186:189], v[40:43]
	v_mfma_f32_16x16x32_bf16 v[36:39], v[170:173], v[186:189], v[36:39]
	v_mfma_f32_16x16x32_bf16 v[24:27], v[162:165], v[204:207], v[24:27]
	v_mfma_f32_16x16x32_bf16 v[20:23], v[170:173], v[204:207], v[20:23]
	v_mfma_f32_16x16x32_bf16 v[8:11], v[162:165], v[212:215], v[8:11]
	v_mfma_f32_16x16x32_bf16 v[4:7], v[170:173], v[212:215], v[4:7]
	v_mfma_f32_16x16x32_bf16 v[56:59], v[166:169], v[182:185], v[56:59]
	v_mfma_f32_16x16x32_bf16 v[52:55], v[174:177], v[182:185], v[52:55]
	v_mfma_f32_16x16x32_bf16 v[40:43], v[166:169], v[190:193], v[40:43]
	v_mfma_f32_16x16x32_bf16 v[36:39], v[174:177], v[190:193], v[36:39]
	v_mfma_f32_16x16x32_bf16 v[24:27], v[166:169], v[208:211], v[24:27]
	v_mfma_f32_16x16x32_bf16 v[20:23], v[174:177], v[208:211], v[20:23]
	v_mfma_f32_16x16x32_bf16 v[8:11], v[166:169], v[230:233], v[8:11]
	v_mfma_f32_16x16x32_bf16 v[4:7], v[174:177], v[230:233], v[4:7]
	s_setprio 0
	s_barrier
	s_add_u32 s82, s82, 0x100
	s_addc_u32 s83, s83, 0
	s_add_u32 s42, s42, 0x100
	s_addc_u32 s43, s43, 0
	s_cmp_ge_i32 s85, s79
	s_mov_b32 s54, s85
	s_cbranch_scc0 .LBB0_1184
	s_and_b64 vcc, exec, s[8:9]
	s_cbranch_vccz .LBB0_1187
	s_barrier

; #define PG8_STAGE(bufoff, gbase, voff) do { _Pragma("unroll") for (int _i = 0; _i < 2; ++_i) \
;         __builtin_amdgcn_global_load_lds((const unsigned*)((const char*)(gbase) + (voff)[_i]), (LAS unsigned*)(lds + (bufoff) + ldsw + _i * 8192), 16, 0, 0); } while (0)
; #define PG8_LDA(dst, b, h) do { _Pragma("unroll") for (int m = 0; m < 4; ++m) _Pragma("unroll") for (int k = 0; k < 2; ++k) dst[m][k] = *(const LAS bf16x8*)(lds + PG8_SA(b, h) + aoff + m * 2048 + k * 1024); } while (0)
; #define PG8_LDB(dst, b, h) do { _Pragma("unroll") for (int n = 0; n < 2; ++n) _Pragma("unroll") for (int k = 0; k < 2; ++k) dst[n][k] = *(const LAS bf16x8*)(lds + PG8_SB(b, h) + boff + n * 2048 + k * 1024); } while (0)
; #define PG8_MMA(ai, bj, At, Bt) do { __builtin_amdgcn_s_setprio(1); _Pragma("unroll") for (int m = 0; m < 4; ++m) _Pragma("unroll") for (int n = 0; n < 2; ++n) _Pragma("unroll") for (int k = 0; k < 2; ++k) \
;         acc[ai][bj][m][n] = __builtin_amdgcn_mfma_f32_16x16x32_bf16(Bt[n][k], At[m][k], acc[ai][bj][m][n], 0, 0, 0); __builtin_amdgcn_s_setprio(0); } while (0)
; #define PG8_WAIT_V(n) asm volatile("s_waitcnt vmcnt(" #n ")" ::: "memory")
; #define PG8_WAIT_L(n) asm volatile("s_waitcnt lgkmcnt(" #n ")" ::: "memory")
; #define PG8_BAR __builtin_amdgcn_s_barrier()
; template <class Epi, class Sched>
; DI void gemm_phase(LAS unsigned char* lds, const Sched& S, const Epi& E) {
;     ...
;             const bool last = (t == nt - 2);
;             const char* a1 = cA + (size_t)(t + 1) * kstep;
;             const char* a2 = last ? nA : cA + (size_t)(t + 2) * kstep; const char* b2 = last ? nB : cB + (size_t)(t + 2) * kstep;
;             const char* a3 = a2 + kstep; const char* b3 = b2 + kstep;
;             if constexpr (Epi::HOOK) { if (cur.ks < 0 && (t == 16 || t == 32)) E.hook(acc, cur, t >> 4, wr, wc, fr, fq); }
;             PG8_LDB(B0, 0, 0); PG8_LDB(B1, 0, 1); PG8_SCHED; PG8_LDA(At, 0, 0); PG8_STAGE(PG8_SA(1, 1), a1 + hstepA, voffA);
;             PG8_WAIT_V(8); PG8_WAIT_L(0); PG8_BAR; PG8_MMA(0, 0, At, B0); PG8_MMA(0, 1, At, B1); PG8_BAR; PG8_SCHED;
;             PG8_LDA(At, 0, 1); PG8_STAGE(PG8_SB(0, 0), b2, voffB); PG8_STAGE(PG8_SB(0, 1), b2 + hstepB, voffB); PG8_STAGE(PG8_SA(0, 0), a2, voffA);
;             PG8_WAIT_V(8); PG8_WAIT_L(0); PG8_BAR; PG8_MMA(1, 0, At, B0); PG8_MMA(1, 1, At, B1); PG8_BAR; PG8_SCHED;
.LBB0_1470:
	s_add_i32 s82, s52, 2
	s_add_u32 s53, s42, 0xffe00080
	s_addc_u32 s54, s43, -1
	s_add_i32 s83, 0, 0x10000
	s_cmp_eq_u32 s79, s52
	s_cselect_b32 s55, s56, s54
	s_cselect_b32 s54, s57, s53
	s_cselect_b32 s53, s58, s81
	s_cselect_b32 s52, s59, s80
	s_add_i32 s85, 0, 0x14000
	v_add_u32_e32 v112, s83, v197
	v_add_u32_e32 v160, s85, v197
	ds_read_b128 v[84:87], v112
	ds_read_b128 v[88:91], v112 offset:1024
	ds_read_b128 v[104:107], v112 offset:2048
	ds_read_b128 v[112:115], v112 offset:3072
	ds_read_b128 v[124:127], v160
	ds_read_b128 v[136:139], v160 offset:1024
	ds_read_b128 v[148:151], v160 offset:2048
	ds_read_b128 v[160:163], v160 offset:3072
	s_add_i32 m0, s61, 0xc000
	ds_read_b128 v[164:167], v231
	ds_read_b128 v[168:171], v231 offset:1024
	ds_read_b128 v[172:175], v231 offset:2048
	ds_read_b128 v[176:179], v231 offset:3072
	ds_read_b128 v[180:183], v231 offset:4096
	ds_read_b128 v[184:187], v231 offset:5120
	ds_read_b128 v[188:191], v231 offset:6144
	ds_read_b128 v[192:195], v231 offset:7168
	global_load_lds_dwordx4 v212, s[42:43]
	s_add_i32 m0, s61, 0xe000
	s_nop 0
	global_load_lds_dwordx4 v210, s[42:43]
	s_waitcnt vmcnt(8)
	s_waitcnt lgkmcnt(0)
	s_barrier
	s_setprio 1
	s_waitcnt lgkmcnt(0)
	v_mfma_f32_16x16x32_bf16 v[156:159], v[84:87], v[164:167], v[156:159]
	v_mfma_f32_16x16x32_bf16 v[152:155], v[104:107], v[164:167], v[152:155]
	v_mfma_f32_16x16x32_bf16 v[132:135], v[84:87], v[172:175], v[132:135]
	v_mfma_f32_16x16x32_bf16 v[128:131], v[104:107], v[172:175], v[128:131]
	v_mfma_f32_16x16x32_bf16 v[108:111], v[84:87], v[180:183], v[108:111]
	v_mfma_f32_16x16x32_bf16 v[100:103], v[104:107], v[180:183], v[100:103]
	v_mfma_f32_16x16x32_bf16 v[80:83], v[84:87], v[188:191], v[80:83]
	v_mfma_f32_16x16x32_bf16 v[76:79], v[104:107], v[188:191], v[76:79]
	v_mfma_f32_16x16x32_bf16 v[156:159], v[88:91], v[168:171], v[156:159]
	v_mfma_f32_16x16x32_bf16 v[152:155], v[112:115], v[168:171], v[152:155]
	v_mfma_f32_16x16x32_bf16 v[132:135], v[88:91], v[176:179], v[132:135]
	v_mfma_f32_16x16x32_bf16 v[128:131], v[112:115], v[176:179], v[128:131]
	v_mfma_f32_16x16x32_bf16 v[108:111], v[88:91], v[184:187], v[108:111]
	v_mfma_f32_16x16x32_bf16 v[100:103], v[112:115], v[184:187], v[100:103]
	v_mfma_f32_16x16x32_bf16 v[80:83], v[88:91], v[192:195], v[80:83]
	v_mfma_f32_16x16x32_bf16 v[76:79], v[112:115], v[192:195], v[76:79]
	s_setprio 0
	s_setprio 1
	v_mfma_f32_16x16x32_bf16 v[144:147], v[124:127], v[164:167], v[144:147]
	v_mfma_f32_16x16x32_bf16 v[140:143], v[148:151], v[164:167], v[140:143]
	v_mfma_f32_16x16x32_bf16 v[120:123], v[124:127], v[172:175], v[120:123]
	v_mfma_f32_16x16x32_bf16 v[116:119], v[148:151], v[172:175], v[116:119]
	v_mfma_f32_16x16x32_bf16 v[96:99], v[124:127], v[180:183], v[96:99]
	v_mfma_f32_16x16x32_bf16 v[92:95], v[148:151], v[180:183], v[92:95]
	v_mfma_f32_16x16x32_bf16 v[72:75], v[124:127], v[188:191], v[72:75]
	v_mfma_f32_16x16x32_bf16 v[68:71], v[148:151], v[188:191], v[68:71]
	v_mfma_f32_16x16x32_bf16 v[144:147], v[136:139], v[168:171], v[144:147]
	v_mfma_f32_16x16x32_bf16 v[140:143], v[160:163], v[168:171], v[140:143]
	v_mfma_f32_16x16x32_bf16 v[120:123], v[136:139], v[176:179], v[120:123]
	v_mfma_f32_16x16x32_bf16 v[116:119], v[160:163], v[176:179], v[116:119]
	v_mfma_f32_16x16x32_bf16 v[96:99], v[136:139], v[184:187], v[96:99]
	v_mfma_f32_16x16x32_bf16 v[92:95], v[160:163], v[184:187], v[92:95]
	v_mfma_f32_16x16x32_bf16 v[72:75], v[136:139], v[192:195], v[72:75]
	v_mfma_f32_16x16x32_bf16 v[68:71], v[160:163], v[192:195], v[68:71]
	s_setprio 0
	s_barrier
	s_add_i32 s83, s83, s60
	s_mov_b32 m0, s83
	ds_read_b128 v[164:167], v231 offset:16384
	ds_read_b128 v[168:171], v231 offset:17408
	ds_read_b128 v[172:175], v231 offset:18432
	ds_read_b128 v[176:179], v231 offset:19456
	ds_read_b128 v[180:183], v231 offset:20480
	ds_read_b128 v[184:187], v231 offset:21504
	ds_read_b128 v[188:191], v231 offset:22528
	ds_read_b128 v[192:195], v231 offset:23552
	global_load_lds_dwordx4 v2, s[52:53]
	s_add_i32 m0, s83, 0x2000
	s_add_u32 s86, s52, 0x200000
	s_addc_u32 s87, s53, 0
	s_add_i32 s83, s85, s60
	global_load_lds_dwordx4 v208, s[52:53]
	s_mov_b32 m0, s83
	s_nop 0
	global_load_lds_dwordx4 v2, s[86:87]
	s_add_i32 m0, s83, 0x2000
	s_nop 0
	global_load_lds_dwordx4 v208, s[86:87]
	s_add_u32 s98, s54, 0x80
	s_addc_u32 s99, s55, 0
	s_mov_b32 m0, s61
	s_nop 0
	global_load_lds_dwordx4 v204, s[54:55]
	s_mov_b32 m0, s62
	s_nop 0
	global_load_lds_dwordx4 v206, s[54:55]
	s_waitcnt vmcnt(8)
	s_waitcnt lgkmcnt(0)
	s_barrier
; #define PG8_STAGE(bufoff, gbase, voff) do { _Pragma("unroll") for (int _i = 0; _i < 2; ++_i) \
;         __builtin_amdgcn_global_load_lds((const unsigned*)((const char*)(gbase) + (voff)[_i]), (LAS unsigned*)(lds + (bufoff) + ldsw + _i * 8192), 16, 0, 0); } while (0)
; #define PG8_LDA(dst, b, h) do { _Pragma("unroll") for (int m = 0; m < 4; ++m) _Pragma("unroll") for (int k = 0; k < 2; ++k) dst[m][k] = *(const LAS bf16x8*)(lds + PG8_SA(b, h) + aoff + m * 2048 + k * 1024); } while (0)
; #define PG8_LDB(dst, b, h) do { _Pragma("unroll") for (int n = 0; n < 2; ++n) _Pragma("unroll") for (int k = 0; k < 2; ++k) dst[n][k] = *(const LAS bf16x8*)(lds + PG8_SB(b, h) + boff + n * 2048 + k * 1024); } while (0)
; #define PG8_MMA(ai, bj, At, Bt) do { __builtin_amdgcn_s_setprio(1); _Pragma("unroll") for (int m = 0; m < 4; ++m) _Pragma("unroll") for (int n = 0; n < 2; ++n) _Pragma("unroll") for (int k = 0; k < 2; ++k) \
;         acc[ai][bj][m][n] = __builtin_amdgcn_mfma_f32_16x16x32_bf16(Bt[n][k], At[m][k], acc[ai][bj][m][n], 0, 0, 0); __builtin_amdgcn_s_setprio(0); } while (0)
; #define PG8_WAIT_V(n) asm volatile("s_waitcnt vmcnt(" #n ")" ::: "memory")
; #define PG8_WAIT_L(n) asm volatile("s_waitcnt lgkmcnt(" #n ")" ::: "memory")
; #define PG8_BAR __builtin_amdgcn_s_barrier()
; #define PG8_SCHED __builtin_amdgcn_sched_barrier(0)
; template <class Epi, class Sched>
; DI void gemm_phase(LAS unsigned char* lds, const Sched& S, const Epi& E) {
;     ...
;             PG8_WAIT_V(8); PG8_WAIT_L(0); PG8_BAR; PG8_MMA(1, 0, At, B0); PG8_MMA(1, 1, At, B1); PG8_BAR; PG8_SCHED;
;             PG8_LDB(B0, 1, 0); PG8_LDB(B1, 1, 1); PG8_SCHED; PG8_LDA(At, 1, 0); PG8_STAGE(PG8_SA(0, 1), a2 + hstepA, voffA);
;             PG8_WAIT_V(8); PG8_WAIT_L(0); PG8_BAR; PG8_MMA(0, 0, At, B0); PG8_MMA(0, 1, At, B1); PG8_BAR; PG8_SCHED;
	s_setprio 1
	s_waitcnt lgkmcnt(0)
	v_mfma_f32_16x16x32_bf16 v[64:67], v[84:87], v[164:167], v[64:67]
	v_mfma_f32_16x16x32_bf16 v[60:63], v[104:107], v[164:167], v[60:63]
	v_mfma_f32_16x16x32_bf16 v[48:51], v[84:87], v[172:175], v[48:51]
	v_mfma_f32_16x16x32_bf16 v[44:47], v[104:107], v[172:175], v[44:47]
	v_mfma_f32_16x16x32_bf16 v[32:35], v[84:87], v[180:183], v[32:35]
	v_mfma_f32_16x16x32_bf16 v[28:31], v[104:107], v[180:183], v[28:31]
	v_mfma_f32_16x16x32_bf16 v[16:19], v[84:87], v[188:191], v[16:19]
	v_mfma_f32_16x16x32_bf16 v[12:15], v[104:107], v[188:191], v[12:15]
	v_mfma_f32_16x16x32_bf16 v[64:67], v[88:91], v[168:171], v[64:67]
	v_mfma_f32_16x16x32_bf16 v[60:63], v[112:115], v[168:171], v[60:63]
	v_mfma_f32_16x16x32_bf16 v[48:51], v[88:91], v[176:179], v[48:51]
	v_mfma_f32_16x16x32_bf16 v[44:47], v[112:115], v[176:179], v[44:47]
	v_mfma_f32_16x16x32_bf16 v[32:35], v[88:91], v[184:187], v[32:35]
	v_mfma_f32_16x16x32_bf16 v[28:31], v[112:115], v[184:187], v[28:31]
	v_mfma_f32_16x16x32_bf16 v[16:19], v[88:91], v[192:195], v[16:19]
	v_mfma_f32_16x16x32_bf16 v[12:15], v[112:115], v[192:195], v[12:15]
	s_setprio 0
	s_setprio 1
	v_mfma_f32_16x16x32_bf16 v[56:59], v[124:127], v[164:167], v[56:59]
	v_mfma_f32_16x16x32_bf16 v[52:55], v[148:151], v[164:167], v[52:55]
	v_mfma_f32_16x16x32_bf16 v[40:43], v[124:127], v[172:175], v[40:43]
	v_mfma_f32_16x16x32_bf16 v[36:39], v[148:151], v[172:175], v[36:39]
	v_mfma_f32_16x16x32_bf16 v[24:27], v[124:127], v[180:183], v[24:27]
	v_mfma_f32_16x16x32_bf16 v[20:23], v[148:151], v[180:183], v[20:23]
	v_mfma_f32_16x16x32_bf16 v[8:11], v[124:127], v[188:191], v[8:11]
	v_mfma_f32_16x16x32_bf16 v[4:7], v[148:151], v[188:191], v[4:7]
	v_mfma_f32_16x16x32_bf16 v[56:59], v[136:139], v[168:171], v[56:59]
	v_mfma_f32_16x16x32_bf16 v[52:55], v[160:163], v[168:171], v[52:55]
	v_mfma_f32_16x16x32_bf16 v[40:43], v[136:139], v[176:179], v[40:43]
	v_mfma_f32_16x16x32_bf16 v[36:39], v[160:163], v[176:179], v[36:39]
	v_mfma_f32_16x16x32_bf16 v[24:27], v[136:139], v[184:187], v[24:27]
	v_mfma_f32_16x16x32_bf16 v[20:23], v[160:163], v[184:187], v[20:23]
	v_mfma_f32_16x16x32_bf16 v[8:11], v[136:139], v[192:195], v[8:11]
	v_mfma_f32_16x16x32_bf16 v[4:7], v[160:163], v[192:195], v[4:7]
	s_setprio 0
	s_barrier
	s_add_i32 s83, 0, 0x18000
	s_add_i32 s85, 0, 0x1c000
	v_add_u32_e32 v112, s83, v197
	v_add_u32_e32 v160, s85, v197
	ds_read_b128 v[84:87], v112
	ds_read_b128 v[88:91], v112 offset:1024
	ds_read_b128 v[104:107], v112 offset:2048
	ds_read_b128 v[112:115], v112 offset:3072
	ds_read_b128 v[124:127], v160
	ds_read_b128 v[136:139], v160 offset:1024
	ds_read_b128 v[148:151], v160 offset:2048
	ds_read_b128 v[160:163], v160 offset:3072
	s_add_u32 s54, s54, 0x200000
	s_addc_u32 s55, s55, 0
	s_mov_b32 m0, s63
	ds_read_b128 v[164:167], v231 offset:32768
	ds_read_b128 v[168:171], v231 offset:33792
	ds_read_b128 v[172:175], v231 offset:34816
	ds_read_b128 v[176:179], v231 offset:35840
	ds_read_b128 v[180:183], v231 offset:36864
	ds_read_b128 v[184:187], v231 offset:37888
	ds_read_b128 v[188:191], v231 offset:38912
	ds_read_b128 v[192:195], v231 offset:39936
	global_load_lds_dwordx4 v204, s[54:55]
	s_mov_b32 m0, s64
	s_nop 0
	global_load_lds_dwordx4 v206, s[54:55]
	s_waitcnt vmcnt(8)
	s_waitcnt lgkmcnt(0)
	s_barrier
	s_setprio 1
	s_waitcnt lgkmcnt(0)
	v_mfma_f32_16x16x32_bf16 v[156:159], v[84:87], v[164:167], v[156:159]
	v_mfma_f32_16x16x32_bf16 v[152:155], v[104:107], v[164:167], v[152:155]
	v_mfma_f32_16x16x32_bf16 v[132:135], v[84:87], v[172:175], v[132:135]
	v_mfma_f32_16x16x32_bf16 v[128:131], v[104:107], v[172:175], v[128:131]
	v_mfma_f32_16x16x32_bf16 v[108:111], v[84:87], v[180:183], v[108:111]
	v_mfma_f32_16x16x32_bf16 v[100:103], v[104:107], v[180:183], v[100:103]
	v_mfma_f32_16x16x32_bf16 v[80:83], v[84:87], v[188:191], v[80:83]
	v_mfma_f32_16x16x32_bf16 v[76:79], v[104:107], v[188:191], v[76:79]
	v_mfma_f32_16x16x32_bf16 v[156:159], v[88:91], v[168:171], v[156:159]
	v_mfma_f32_16x16x32_bf16 v[152:155], v[112:115], v[168:171], v[152:155]
	v_mfma_f32_16x16x32_bf16 v[132:135], v[88:91], v[176:179], v[132:135]
	v_mfma_f32_16x16x32_bf16 v[128:131], v[112:115], v[176:179], v[128:131]
	v_mfma_f32_16x16x32_bf16 v[108:111], v[88:91], v[184:187], v[108:111]
	v_mfma_f32_16x16x32_bf16 v[100:103], v[112:115], v[184:187], v[100:103]
	v_mfma_f32_16x16x32_bf16 v[80:83], v[88:91], v[192:195], v[80:83]
	v_mfma_f32_16x16x32_bf16 v[76:79], v[112:115], v[192:195], v[76:79]
	s_setprio 0
	s_setprio 1
	v_mfma_f32_16x16x32_bf16 v[144:147], v[124:127], v[164:167], v[144:147]
	v_mfma_f32_16x16x32_bf16 v[140:143], v[148:151], v[164:167], v[140:143]
	v_mfma_f32_16x16x32_bf16 v[120:123], v[124:127], v[172:175], v[120:123]
	v_mfma_f32_16x16x32_bf16 v[116:119], v[148:151], v[172:175], v[116:119]
	v_mfma_f32_16x16x32_bf16 v[96:99], v[124:127], v[180:183], v[96:99]
	v_mfma_f32_16x16x32_bf16 v[92:95], v[148:151], v[180:183], v[92:95]
	v_mfma_f32_16x16x32_bf16 v[72:75], v[124:127], v[188:191], v[72:75]
	v_mfma_f32_16x16x32_bf16 v[68:71], v[148:151], v[188:191], v[68:71]
	v_mfma_f32_16x16x32_bf16 v[144:147], v[136:139], v[168:171], v[144:147]
	v_mfma_f32_16x16x32_bf16 v[140:143], v[160:163], v[168:171], v[140:143]
	v_mfma_f32_16x16x32_bf16 v[120:123], v[136:139], v[176:179], v[120:123]
	v_mfma_f32_16x16x32_bf16 v[116:119], v[160:163], v[176:179], v[116:119]
	v_mfma_f32_16x16x32_bf16 v[96:99], v[136:139], v[184:187], v[96:99]
	v_mfma_f32_16x16x32_bf16 v[92:95], v[160:163], v[184:187], v[92:95]
	v_mfma_f32_16x16x32_bf16 v[72:75], v[136:139], v[192:195], v[72:75]
	v_mfma_f32_16x16x32_bf16 v[68:71], v[160:163], v[192:195], v[68:71]
	s_setprio 0
	s_barrier
; #define PG8_STAGE(bufoff, gbase, voff) do { _Pragma("unroll") for (int _i = 0; _i < 2; ++_i) \
;         __builtin_amdgcn_global_load_lds((const unsigned*)((const char*)(gbase) + (voff)[_i]), (LAS unsigned*)(lds + (bufoff) + ldsw + _i * 8192), 16, 0, 0); } while (0)
; #define PG8_LDA(dst, b, h) do { _Pragma("unroll") for (int m = 0; m < 4; ++m) _Pragma("unroll") for (int k = 0; k < 2; ++k) dst[m][k] = *(const LAS bf16x8*)(lds + PG8_SA(b, h) + aoff + m * 2048 + k * 1024); } while (0)
; #define PG8_MMA(ai, bj, At, Bt) do { __builtin_amdgcn_s_setprio(1); _Pragma("unroll") for (int m = 0; m < 4; ++m) _Pragma("unroll") for (int n = 0; n < 2; ++n) _Pragma("unroll") for (int k = 0; k < 2; ++k) \
;         acc[ai][bj][m][n] = __builtin_amdgcn_mfma_f32_16x16x32_bf16(Bt[n][k], At[m][k], acc[ai][bj][m][n], 0, 0, 0); __builtin_amdgcn_s_setprio(0); } while (0)
; #define PG8_WAIT_V(n) asm volatile("s_waitcnt vmcnt(" #n ")" ::: "memory")
; #define PG8_WAIT_L(n) asm volatile("s_waitcnt lgkmcnt(" #n ")" ::: "memory")
; #define PG8_BAR __builtin_amdgcn_s_barrier()
; #define PG8_SCHED __builtin_amdgcn_sched_barrier(0)
; template <class Epi, class Sched>
; DI void gemm_phase(LAS unsigned char* lds, const Sched& S, const Epi& E) {
;     ...
;             PG8_LDA(At, 1, 1); PG8_STAGE(PG8_SB(1, 0), b3, voffB); PG8_STAGE(PG8_SB(1, 1), b3 + hstepB, voffB); PG8_STAGE(PG8_SA(1, 0), a3, voffA);
;             PG8_WAIT_V(8); PG8_WAIT_L(0); PG8_BAR; PG8_MMA(1, 0, At, B0); PG8_MMA(1, 1, At, B1); PG8_BAR; PG8_SCHED;
;         }
	s_add_i32 s54, s83, s60
	s_add_u32 s52, s52, 0x80
	s_addc_u32 s53, s53, 0
	s_mov_b32 m0, s54
	ds_read_b128 v[164:167], v231 offset:49152
	ds_read_b128 v[168:171], v231 offset:50176
	ds_read_b128 v[172:175], v231 offset:51200
	ds_read_b128 v[176:179], v231 offset:52224
	ds_read_b128 v[180:183], v231 offset:53248
	ds_read_b128 v[184:187], v231 offset:54272
	ds_read_b128 v[188:191], v231 offset:55296
	ds_read_b128 v[192:195], v231 offset:56320
	global_load_lds_dwordx4 v2, s[52:53]
	s_add_i32 m0, s54, 0x2000
	s_add_i32 s54, s85, s60
	global_load_lds_dwordx4 v208, s[52:53]
	s_add_u32 s52, s52, 0x200000
	s_addc_u32 s53, s53, 0
	s_mov_b32 m0, s54
	s_nop 0
	global_load_lds_dwordx4 v2, s[52:53]
	s_add_i32 m0, s54, 0x2000
	s_nop 0
	global_load_lds_dwordx4 v208, s[52:53]
	s_mov_b32 m0, s71
	s_nop 0
	global_load_lds_dwordx4 v204, s[98:99]
	s_mov_b32 m0, s72
	s_nop 0
	global_load_lds_dwordx4 v206, s[98:99]
	s_waitcnt vmcnt(8)
	s_waitcnt lgkmcnt(0)
	s_barrier
	s_setprio 1
	s_waitcnt lgkmcnt(0)
	v_mfma_f32_16x16x32_bf16 v[64:67], v[84:87], v[164:167], v[64:67]
	v_mfma_f32_16x16x32_bf16 v[60:63], v[104:107], v[164:167], v[60:63]
	v_mfma_f32_16x16x32_bf16 v[48:51], v[84:87], v[172:175], v[48:51]
	v_mfma_f32_16x16x32_bf16 v[44:47], v[104:107], v[172:175], v[44:47]
	v_mfma_f32_16x16x32_bf16 v[32:35], v[84:87], v[180:183], v[32:35]
	v_mfma_f32_16x16x32_bf16 v[28:31], v[104:107], v[180:183], v[28:31]
	v_mfma_f32_16x16x32_bf16 v[16:19], v[84:87], v[188:191], v[16:19]
	v_mfma_f32_16x16x32_bf16 v[12:15], v[104:107], v[188:191], v[12:15]
	v_mfma_f32_16x16x32_bf16 v[64:67], v[88:91], v[168:171], v[64:67]
	v_mfma_f32_16x16x32_bf16 v[60:63], v[112:115], v[168:171], v[60:63]
	v_mfma_f32_16x16x32_bf16 v[48:51], v[88:91], v[176:179], v[48:51]
	v_mfma_f32_16x16x32_bf16 v[44:47], v[112:115], v[176:179], v[44:47]
	v_mfma_f32_16x16x32_bf16 v[32:35], v[88:91], v[184:187], v[32:35]
	v_mfma_f32_16x16x32_bf16 v[28:31], v[112:115], v[184:187], v[28:31]
	v_mfma_f32_16x16x32_bf16 v[16:19], v[88:91], v[192:195], v[16:19]
	v_mfma_f32_16x16x32_bf16 v[12:15], v[112:115], v[192:195], v[12:15]
	s_setprio 0
	s_setprio 1
	v_mfma_f32_16x16x32_bf16 v[56:59], v[124:127], v[164:167], v[56:59]
	v_mfma_f32_16x16x32_bf16 v[52:55], v[148:151], v[164:167], v[52:55]
	v_mfma_f32_16x16x32_bf16 v[40:43], v[124:127], v[172:175], v[40:43]
	v_mfma_f32_16x16x32_bf16 v[36:39], v[148:151], v[172:175], v[36:39]
	v_mfma_f32_16x16x32_bf16 v[24:27], v[124:127], v[180:183], v[24:27]
	v_mfma_f32_16x16x32_bf16 v[20:23], v[148:151], v[180:183], v[20:23]
	v_mfma_f32_16x16x32_bf16 v[8:11], v[124:127], v[188:191], v[8:11]
	v_mfma_f32_16x16x32_bf16 v[4:7], v[148:151], v[188:191], v[4:7]
	v_mfma_f32_16x16x32_bf16 v[56:59], v[136:139], v[168:171], v[56:59]
	v_mfma_f32_16x16x32_bf16 v[52:55], v[160:163], v[168:171], v[52:55]
	v_mfma_f32_16x16x32_bf16 v[40:43], v[136:139], v[176:179], v[40:43]
	v_mfma_f32_16x16x32_bf16 v[36:39], v[160:163], v[176:179], v[36:39]
	v_mfma_f32_16x16x32_bf16 v[24:27], v[136:139], v[184:187], v[24:27]
	v_mfma_f32_16x16x32_bf16 v[20:23], v[160:163], v[184:187], v[20:23]
	v_mfma_f32_16x16x32_bf16 v[8:11], v[136:139], v[192:195], v[8:11]
	v_mfma_f32_16x16x32_bf16 v[4:7], v[160:163], v[192:195], v[4:7]
	s_setprio 0
	s_barrier
	s_add_u32 s80, s80, 0x100
	s_addc_u32 s81, s81, 0
	s_add_u32 s42, s42, 0x100
	s_addc_u32 s43, s43, 0
	s_cmp_ge_i32 s82, s75
	s_mov_b32 s52, s82
	s_cbranch_scc0 .LBB0_1470
	s_and_b64 vcc, exec, s[38:39]
	s_cbranch_vccz .LBB0_1473
	s_barrier
